# E_GU pair tiles 128x256 (shared A operand, 3-slot ring, half-stage frag double-buffer), LDS 80KB
# speedup vs baseline: 1.0981x; 1.0148x over previous
.LBB0_116:
	s_andn2_b64 vcc, exec, s[0:1]
	s_cbranch_vccnz .LBB0_143
	s_mov_b32 s63, 2
	s_mov_b32 s62, 0
	s_load_dword s0, s[96:97], 0x0
	s_and_b32 s22, s74, 7
	s_waitcnt lgkmcnt(0)
	s_lshr_b32 s13, s0, 6
	v_cvt_f32_u32_e32 v0, s13
	s_sub_i32 s1, 0, s13
	s_add_i32 s0, s13, 43
	v_rcp_iflag_f32_e32 v0, v0
	s_nop 0
	v_mul_f32_e32 v0, 0x4f7ffffe, v0
	v_cvt_u32_f32_e32 v0, v0
	s_nop 0
	v_readfirstlane_b32 s8, v0
	s_mul_i32 s1, s1, s8
	s_mul_hi_u32 s1, s8, s1
	s_add_i32 s8, s8, s1
	s_mul_hi_u32 s1, s0, s8
	s_mul_i32 s8, s1, s13
	s_sub_i32 s0, s0, s8
	s_add_i32 s9, s1, 1
	s_sub_i32 s8, s0, s13
	s_cmp_ge_u32 s0, s13
	s_cselect_b32 s1, s9, s1
	s_cselect_b32 s0, s8, s0
	s_add_i32 s8, s1, 1
	s_cmp_ge_u32 s0, s13
	s_cselect_b32 s23, s8, s1
	s_mul_i32 s23, s23, 6
	s_cmp_ge_u32 s22, s23
	s_cbranch_scc1 .LBB0_143
	s_cmp_eq_u32 s13, 8
	s_cbranch_scc0 .Lgu_orig1
	s_mov_b32 s63, 0
	s_lshr_b32 s22, s74, 3
	s_movk_i32 s23, 0x88
	s_mov_b64 s[8:9], 0
	s_cmp_lt_u32 s22, 0x80
	s_cbranch_scc0 .Ldec_s1
	s_mul_hi_u32 s1, s22, 0x2aaaaaab
	s_mul_i32 s15, s1, 6
	s_sub_i32 s15, s22, s15
	s_lshl_b32 s1, s1, 1
	s_branch .Ldec_e1
.Ldec_s1:
	s_add_i32 s1, s22, 0xffffff80
	s_lshr_b32 s15, s1, 1
	s_add_i32 s15, s15, 2
	s_and_b32 s1, s1, 1
	s_add_i32 s1, s1, 42
.Ldec_e1:
	s_lshl_b32 s0, s15, 3
	s_and_b32 s15, s74, 7
	s_or_b32 s0, s0, s15
	s_lshl_b32 s0, s0, 7
	s_lshl_b32 s14, s1, 7
	s_add_i32 s22, s22, 64
	s_mov_b64 s[8:9], -1
	s_branch .LBB0_124

.LBB0_126:
	s_cmp_eq_u32 s62, 1
	s_cbranch_scc0 .Lgu_ein
	s_mov_b32 s60, s38
	s_mov_b32 s61, s35
	s_mov_b32 s38, s0
	s_add_i32 s35, s14, 0x80
	s_mov_b32 s62, 2
.Lgu_ein:
	v_cvt_f32_i32_e32 v87, v69
	ds_read_b128 v[108:111], v106
	ds_read_b128 v[112:115], v106 offset:32
	ds_read_b128 v[128:131], v106 offset:64
	ds_read_b128 v[132:135], v106 offset:96
	ds_read_b128 v[76:79], v106 offset:128
	ds_read_b128 v[72:75], v106 offset:160
	v_cvt_f32_i32_e32 v119, v68
	ds_read_b128 v[68:71], v106 offset:192
	ds_read_b128 v[64:67], v106 offset:224
	v_mul_f32_e32 v87, 0x33800000, v87
	s_waitcnt lgkmcnt(0)
	v_fma_f32 v48, v48, v108, v87
	v_fma_f32 v49, v49, v109, v87
	v_fma_f32 v50, v50, v110, v87
	v_fma_f32 v51, v51, v111, v87
	v_fma_f32 v52, v52, v112, v87
	v_fma_f32 v53, v53, v113, v87
	v_fma_f32 v54, v54, v114, v87
	v_fma_f32 v55, v55, v115, v87
	v_fma_f32 v56, v56, v128, v87
	v_fma_f32 v57, v57, v129, v87
	v_fma_f32 v58, v58, v130, v87
	v_fma_f32 v59, v59, v131, v87
	v_fma_f32 v60, v60, v132, v87
	v_fma_f32 v61, v61, v133, v87
	v_fma_f32 v62, v62, v134, v87
	v_fma_f32 v63, v63, v135, v87
	v_mul_f32_e32 v119, 0x33800000, v119
	v_mul_f32_e32 v121, 0xbfb8aa3b, v48
	v_mul_f32_e32 v122, 0xbfb8aa3b, v49
	v_mul_f32_e32 v125, 0xbfb8aa3b, v50
	v_mul_f32_e32 v136, 0xbfb8aa3b, v51
	v_mul_f32_e32 v137, 0xbfb8aa3b, v52
	v_mul_f32_e32 v138, 0xbfb8aa3b, v53
	v_mul_f32_e32 v139, 0xbfb8aa3b, v54
	v_mul_f32_e32 v140, 0xbfb8aa3b, v55
	v_mul_f32_e32 v141, 0xbfb8aa3b, v56
	v_mul_f32_e32 v142, 0xbfb8aa3b, v57
	v_mul_f32_e32 v143, 0xbfb8aa3b, v58
	v_mul_f32_e32 v144, 0xbfb8aa3b, v59
	v_mul_f32_e32 v145, 0xbfb8aa3b, v60
	v_mul_f32_e32 v146, 0xbfb8aa3b, v61
	v_mul_f32_e32 v147, 0xbfb8aa3b, v62
	v_mul_f32_e32 v148, 0xbfb8aa3b, v63
	v_exp_f32_e32 v121, v121
	v_exp_f32_e32 v122, v122
	v_exp_f32_e32 v125, v125
	v_exp_f32_e32 v136, v136
	v_exp_f32_e32 v137, v137
	v_exp_f32_e32 v138, v138
	v_exp_f32_e32 v139, v139
	v_exp_f32_e32 v140, v140
	v_exp_f32_e32 v141, v141
	v_exp_f32_e32 v142, v142
	v_exp_f32_e32 v143, v143
	v_exp_f32_e32 v144, v144
	v_exp_f32_e32 v145, v145
	v_exp_f32_e32 v146, v146
	v_exp_f32_e32 v147, v147
	v_exp_f32_e32 v148, v148
	v_add_f32_e32 v121, 1.0, v121
	v_add_f32_e32 v122, 1.0, v122
	v_add_f32_e32 v125, 1.0, v125
	v_add_f32_e32 v136, 1.0, v136
	v_add_f32_e32 v137, 1.0, v137
	v_add_f32_e32 v138, 1.0, v138
	v_add_f32_e32 v139, 1.0, v139
	v_add_f32_e32 v140, 1.0, v140
	v_add_f32_e32 v141, 1.0, v141
	v_add_f32_e32 v142, 1.0, v142
	v_add_f32_e32 v143, 1.0, v143
	v_add_f32_e32 v144, 1.0, v144
	v_add_f32_e32 v145, 1.0, v145
	v_add_f32_e32 v146, 1.0, v146
	v_add_f32_e32 v147, 1.0, v147
	v_add_f32_e32 v148, 1.0, v148
	v_rcp_f32_e32 v121, v121
	v_rcp_f32_e32 v122, v122
	v_rcp_f32_e32 v125, v125
	v_rcp_f32_e32 v136, v136
	v_rcp_f32_e32 v137, v137
	v_rcp_f32_e32 v138, v138
	v_rcp_f32_e32 v139, v139
	v_rcp_f32_e32 v140, v140
	v_rcp_f32_e32 v141, v141
	v_rcp_f32_e32 v142, v142
	v_rcp_f32_e32 v143, v143
	v_rcp_f32_e32 v144, v144
	v_rcp_f32_e32 v145, v145
	v_rcp_f32_e32 v146, v146
	v_rcp_f32_e32 v147, v147
	v_rcp_f32_e32 v148, v148
	v_mul_f32_e32 v48, v48, v121
	v_fma_f32 v32, v32, v108, v119
	v_mul_f32_e32 v32, v32, v48
	v_mul_f32_e32 v48, v49, v122
	v_fma_f32 v33, v33, v109, v119
	v_mul_f32_e32 v33, v33, v48
	v_mul_f32_e32 v48, v50, v125
	v_fma_f32 v34, v34, v110, v119
	v_cvt_pk_bf16_f32 v32, v32, s0
	v_mul_f32_e32 v34, v34, v48
	v_mul_f32_e32 v48, v51, v136
	v_fma_f32 v35, v35, v111, v119
	ds_write_b16 v107, v32 offset:49152
	v_cvt_pk_bf16_f32 v32, v33, s0
	v_mul_f32_e32 v35, v35, v48
	v_mul_f32_e32 v48, v52, v137
	v_fma_f32 v36, v36, v112, v119
	ds_write_b16 v107, v32 offset:49296
	v_cvt_pk_bf16_f32 v32, v34, s0
	v_mul_f32_e32 v36, v36, v48
	v_mul_f32_e32 v48, v53, v138
	v_fma_f32 v37, v37, v113, v119
	ds_write_b16 v107, v32 offset:49440
	v_cvt_pk_bf16_f32 v32, v35, s0
	v_mul_f32_e32 v37, v37, v48
	v_mul_f32_e32 v48, v54, v139
	v_fma_f32 v38, v38, v114, v119
	ds_write_b16 v107, v32 offset:49584
	v_cvt_pk_bf16_f32 v32, v36, s0
	v_mul_f32_e32 v38, v38, v48
	v_mul_f32_e32 v48, v55, v140
	v_fma_f32 v39, v39, v115, v119
	ds_write_b16 v107, v32 offset:50304
	v_cvt_pk_bf16_f32 v32, v37, s0
	v_mul_f32_e32 v39, v39, v48
	v_mul_f32_e32 v48, v56, v141
	v_fma_f32 v40, v40, v128, v119
	ds_write_b16 v107, v32 offset:50448
	v_cvt_pk_bf16_f32 v32, v38, s0
	v_mul_f32_e32 v40, v40, v48
	v_mul_f32_e32 v48, v57, v142
	v_fma_f32 v41, v41, v129, v119
	ds_write_b16 v107, v32 offset:50592
	v_cvt_pk_bf16_f32 v32, v39, s0
	v_mul_f32_e32 v41, v41, v48
	v_mul_f32_e32 v48, v58, v143
	v_fma_f32 v42, v42, v130, v119
	ds_write_b16 v107, v32 offset:50736
	v_cvt_pk_bf16_f32 v32, v40, s0
	v_mul_f32_e32 v42, v42, v48
	v_mul_f32_e32 v48, v59, v144
	v_fma_f32 v43, v43, v131, v119
	ds_write_b16 v107, v32 offset:51456
	v_cvt_pk_bf16_f32 v32, v41, s0
	v_mul_f32_e32 v43, v43, v48
	v_mul_f32_e32 v48, v60, v145
	v_fma_f32 v44, v44, v132, v119
	ds_write_b16 v107, v32 offset:51600
	v_cvt_pk_bf16_f32 v32, v42, s0
	v_mul_f32_e32 v44, v44, v48
	v_mul_f32_e32 v48, v61, v146
	v_fma_f32 v45, v45, v133, v119
	ds_write_b16 v107, v32 offset:51744
	v_cvt_pk_bf16_f32 v32, v43, s0
	v_mul_f32_e32 v45, v45, v48
	v_mul_f32_e32 v48, v62, v147
	v_fma_f32 v46, v46, v134, v119
	ds_write_b16 v107, v32 offset:51888
	v_cvt_pk_bf16_f32 v32, v44, s0
	v_mul_f32_e32 v46, v46, v48
	v_mul_f32_e32 v48, v63, v148
	v_fma_f32 v47, v47, v135, v119
	ds_write_b16 v107, v32 offset:52608
	v_cvt_pk_bf16_f32 v32, v45, s0
	v_mul_f32_e32 v47, v47, v48
	ds_write_b16 v107, v32 offset:52752
	v_cvt_pk_bf16_f32 v32, v46, s0
	ds_write_b16 v107, v32 offset:52896
	v_cvt_pk_bf16_f32 v32, v47, s0
	v_fma_f32 v16, v16, v76, v87
	v_fma_f32 v17, v17, v77, v87
	v_fma_f32 v18, v18, v78, v87
	v_fma_f32 v19, v19, v79, v87
	v_fma_f32 v20, v20, v72, v87
	v_fma_f32 v21, v21, v73, v87
	v_fma_f32 v22, v22, v74, v87
	v_fma_f32 v23, v23, v75, v87
	v_fma_f32 v24, v24, v68, v87
	v_fma_f32 v25, v25, v69, v87
	v_fma_f32 v26, v26, v70, v87
	v_fma_f32 v27, v27, v71, v87
	v_fma_f32 v28, v28, v64, v87
	v_fma_f32 v29, v29, v65, v87
	v_fma_f32 v30, v30, v66, v87
	v_fmac_f32_e32 v87, v31, v67
	ds_write_b16 v107, v32 offset:53040
	v_mul_f32_e32 v31, 0xbfb8aa3b, v16
	v_mul_f32_e32 v32, 0xbfb8aa3b, v17
	v_mul_f32_e32 v33, 0xbfb8aa3b, v18
	v_mul_f32_e32 v34, 0xbfb8aa3b, v19
	v_mul_f32_e32 v35, 0xbfb8aa3b, v20
	v_mul_f32_e32 v36, 0xbfb8aa3b, v21
	v_mul_f32_e32 v37, 0xbfb8aa3b, v22
	v_mul_f32_e32 v38, 0xbfb8aa3b, v23
	v_mul_f32_e32 v39, 0xbfb8aa3b, v24
	v_mul_f32_e32 v40, 0xbfb8aa3b, v25
	v_mul_f32_e32 v41, 0xbfb8aa3b, v26
	v_mul_f32_e32 v42, 0xbfb8aa3b, v27
	v_mul_f32_e32 v43, 0xbfb8aa3b, v28
	v_mul_f32_e32 v44, 0xbfb8aa3b, v29
	v_mul_f32_e32 v45, 0xbfb8aa3b, v30
	v_mul_f32_e32 v46, 0xbfb8aa3b, v87
	v_exp_f32_e32 v31, v31
	v_exp_f32_e32 v32, v32
	v_exp_f32_e32 v33, v33
	v_exp_f32_e32 v34, v34
	v_exp_f32_e32 v35, v35
	v_exp_f32_e32 v36, v36
	v_exp_f32_e32 v37, v37
	v_exp_f32_e32 v38, v38
	v_exp_f32_e32 v39, v39
	v_exp_f32_e32 v40, v40
	v_exp_f32_e32 v41, v41
	v_exp_f32_e32 v42, v42
	v_exp_f32_e32 v43, v43
	v_exp_f32_e32 v44, v44
	v_exp_f32_e32 v45, v45
	v_exp_f32_e32 v46, v46
	v_add_f32_e32 v31, 1.0, v31
	v_add_f32_e32 v32, 1.0, v32
	v_add_f32_e32 v33, 1.0, v33
	v_add_f32_e32 v34, 1.0, v34
	v_add_f32_e32 v35, 1.0, v35
	v_add_f32_e32 v36, 1.0, v36
	v_add_f32_e32 v37, 1.0, v37
	v_add_f32_e32 v38, 1.0, v38
	v_add_f32_e32 v39, 1.0, v39
	v_add_f32_e32 v40, 1.0, v40
	v_add_f32_e32 v41, 1.0, v41
	v_add_f32_e32 v42, 1.0, v42
	v_add_f32_e32 v43, 1.0, v43
	v_add_f32_e32 v44, 1.0, v44
	v_add_f32_e32 v45, 1.0, v45
	v_add_f32_e32 v46, 1.0, v46
	v_rcp_f32_e32 v31, v31
	v_rcp_f32_e32 v32, v32
	v_rcp_f32_e32 v33, v33
	v_rcp_f32_e32 v34, v34
	v_rcp_f32_e32 v35, v35
	v_rcp_f32_e32 v36, v36
	v_rcp_f32_e32 v37, v37
	v_rcp_f32_e32 v38, v38
	v_rcp_f32_e32 v39, v39
	v_rcp_f32_e32 v40, v40
	v_rcp_f32_e32 v41, v41
	v_rcp_f32_e32 v42, v42
	v_rcp_f32_e32 v43, v43
	v_rcp_f32_e32 v44, v44
	v_rcp_f32_e32 v45, v45
	v_rcp_f32_e32 v46, v46
	v_mul_f32_e32 v16, v16, v31
	v_fma_f32 v0, v0, v76, v119
	v_mul_f32_e32 v0, v0, v16
	v_mul_f32_e32 v16, v17, v32
	v_fma_f32 v1, v1, v77, v119
	v_mul_f32_e32 v1, v1, v16
	v_mul_f32_e32 v16, v18, v33
	v_fma_f32 v2, v2, v78, v119
	v_cvt_pk_bf16_f32 v0, v0, s0
	v_mul_f32_e32 v2, v2, v16
	v_mul_f32_e32 v16, v19, v34
	v_fma_f32 v3, v3, v79, v119
	ds_write_b16 v107, v0 offset:53760
	v_cvt_pk_bf16_f32 v0, v1, s0
	v_mul_f32_e32 v3, v3, v16
	v_mul_f32_e32 v16, v20, v35
	v_fma_f32 v4, v4, v72, v119
	ds_write_b16 v107, v0 offset:53904
	v_cvt_pk_bf16_f32 v0, v2, s0
	v_mul_f32_e32 v4, v4, v16
	v_mul_f32_e32 v16, v21, v36
	v_fma_f32 v5, v5, v73, v119
	ds_write_b16 v107, v0 offset:54048
	v_cvt_pk_bf16_f32 v0, v3, s0
	v_mul_f32_e32 v5, v5, v16
	v_mul_f32_e32 v16, v22, v37
	v_fma_f32 v6, v6, v74, v119
	ds_write_b16 v107, v0 offset:54192
	v_cvt_pk_bf16_f32 v0, v4, s0
	v_mul_f32_e32 v6, v6, v16
	v_mul_f32_e32 v16, v23, v38
	v_fma_f32 v7, v7, v75, v119
	ds_write_b16 v107, v0 offset:54912
	v_cvt_pk_bf16_f32 v0, v5, s0
	v_mul_f32_e32 v7, v7, v16
	v_mul_f32_e32 v16, v24, v39
	v_fma_f32 v8, v8, v68, v119
	ds_write_b16 v107, v0 offset:55056
	v_cvt_pk_bf16_f32 v0, v6, s0
	v_mul_f32_e32 v8, v8, v16
	v_mul_f32_e32 v16, v25, v40
	v_fma_f32 v9, v9, v69, v119
	ds_write_b16 v107, v0 offset:55200
	v_cvt_pk_bf16_f32 v0, v7, s0
	v_mul_f32_e32 v9, v9, v16
	v_mul_f32_e32 v16, v26, v41
	v_fma_f32 v10, v10, v70, v119
	ds_write_b16 v107, v0 offset:55344
	v_cvt_pk_bf16_f32 v0, v8, s0
	v_mul_f32_e32 v10, v10, v16
	v_mul_f32_e32 v16, v27, v42
	v_fma_f32 v11, v11, v71, v119
	ds_write_b16 v107, v0 offset:56064
	v_cvt_pk_bf16_f32 v0, v9, s0
	v_mul_f32_e32 v11, v11, v16
	v_mul_f32_e32 v16, v28, v43
	v_fma_f32 v12, v12, v64, v119
	ds_write_b16 v107, v0 offset:56208
	v_cvt_pk_bf16_f32 v0, v10, s0
	v_mul_f32_e32 v12, v12, v16
	v_mul_f32_e32 v16, v29, v44
	v_fma_f32 v13, v13, v65, v119
	ds_write_b16 v107, v0 offset:56352
	v_cvt_pk_bf16_f32 v0, v11, s0
	v_mul_f32_e32 v13, v13, v16
	v_mul_f32_e32 v16, v30, v45
	v_fma_f32 v14, v14, v66, v119
	ds_write_b16 v107, v0 offset:56496
	v_cvt_pk_bf16_f32 v0, v12, s0
	v_mul_f32_e32 v14, v14, v16
	v_mul_f32_e32 v16, v87, v46
	v_fmac_f32_e32 v119, v15, v67
	ds_write_b16 v107, v0 offset:57216
	v_cvt_pk_bf16_f32 v0, v13, s0
	v_mul_f32_e32 v15, v119, v16
	ds_write_b16 v107, v0 offset:57360
	v_cvt_pk_bf16_f32 v0, v14, s0
	ds_write_b16 v107, v0 offset:57504
	v_cvt_pk_bf16_f32 v0, v15, s0
	v_add_u32_e32 v4, s0, v94
	s_ashr_i32 s1, s14, 1
	ds_write_b16 v107, v0 offset:57648
	v_add_u32_e32 v5, s1, v95
	v_ashrrev_i32_e32 v0, 7, v4
	s_movk_i32 s14, 0x58
	v_mul_lo_u32 v0, v0, s14
	v_ashrrev_i32_e32 v2, 5, v5
	v_ashrrev_i32_e32 v1, 31, v0
	v_ashrrev_i32_e32 v3, 31, v2
	v_lshl_add_u64 v[0:1], v[0:1], 0, v[2:3]
	v_lshlrev_b64 v[0:1], 13, v[0:1]
	v_lshlrev_b32_e32 v2, 6, v4
	v_and_b32_e32 v5, 31, v5
	v_lshl_add_u64 v[0:1], s[8:9], 0, v[0:1]
	v_and_b32_e32 v2, 0x1fc0, v2
	v_mov_b32_e32 v3, v117
	v_lshl_add_u64 v[0:1], v[0:1], 0, v[2:3]
	v_lshlrev_b32_e32 v2, 1, v5
	s_waitcnt lgkmcnt(0)
	s_barrier
	v_lshl_add_u64 v[4:5], v[0:1], 0, v[2:3]
	ds_read_b128 v[0:3], v96 offset:49152
	s_mov_b64 s[18:19], -1
	s_and_b64 vcc, exec, s[10:11]
	s_waitcnt lgkmcnt(0)
	global_store_dwordx4 v[4:5], v[0:3], off
	v_add_u32_e32 v4, s0, v97
	v_add_u32_e32 v5, s1, v98
	v_ashrrev_i32_e32 v0, 7, v4
	v_mul_lo_u32 v0, v0, s14
	v_ashrrev_i32_e32 v2, 5, v5
	v_ashrrev_i32_e32 v1, 31, v0
	v_ashrrev_i32_e32 v3, 31, v2
	v_lshl_add_u64 v[0:1], v[0:1], 0, v[2:3]
	v_lshlrev_b64 v[0:1], 13, v[0:1]
	v_lshlrev_b32_e32 v2, 6, v4
	v_and_b32_e32 v5, 31, v5
	v_lshl_add_u64 v[0:1], s[8:9], 0, v[0:1]
	v_and_b32_e32 v2, 0x1fc0, v2
	v_mov_b32_e32 v3, v117
	v_lshl_add_u64 v[0:1], v[0:1], 0, v[2:3]
	v_lshlrev_b32_e32 v2, 1, v5
	v_lshl_add_u64 v[4:5], v[0:1], 0, v[2:3]
	ds_read_b128 v[0:3], v99 offset:49152
	s_waitcnt lgkmcnt(0)
	global_store_dwordx4 v[4:5], v[0:3], off
	v_add_u32_e32 v4, s0, v100
	v_add_u32_e32 v5, s1, v101
	v_ashrrev_i32_e32 v0, 7, v4
	v_mul_lo_u32 v0, v0, s14
	v_ashrrev_i32_e32 v2, 5, v5
	v_ashrrev_i32_e32 v1, 31, v0
	v_ashrrev_i32_e32 v3, 31, v2
	v_lshl_add_u64 v[0:1], v[0:1], 0, v[2:3]
	v_lshlrev_b64 v[0:1], 13, v[0:1]
	v_lshlrev_b32_e32 v2, 6, v4
	v_and_b32_e32 v5, 31, v5
	v_lshl_add_u64 v[0:1], s[8:9], 0, v[0:1]
	v_and_b32_e32 v2, 0x1fc0, v2
	v_mov_b32_e32 v3, v117
	v_lshl_add_u64 v[0:1], v[0:1], 0, v[2:3]
	v_lshlrev_b32_e32 v2, 1, v5
	v_lshl_add_u64 v[4:5], v[0:1], 0, v[2:3]
	ds_read_b128 v[0:3], v102 offset:49152
	s_waitcnt lgkmcnt(0)
	global_store_dwordx4 v[4:5], v[0:3], off
	v_add_u32_e32 v4, s0, v103
	v_add_u32_e32 v5, s1, v104
	v_ashrrev_i32_e32 v0, 7, v4
	v_mul_lo_u32 v0, v0, s14
	v_ashrrev_i32_e32 v2, 5, v5
	v_ashrrev_i32_e32 v1, 31, v0
	v_ashrrev_i32_e32 v3, 31, v2
	v_lshl_add_u64 v[0:1], v[0:1], 0, v[2:3]
	v_lshlrev_b64 v[0:1], 13, v[0:1]
	v_lshlrev_b32_e32 v2, 6, v4
	v_and_b32_e32 v5, 31, v5
	v_lshl_add_u64 v[0:1], s[8:9], 0, v[0:1]
	v_and_b32_e32 v2, 0x1fc0, v2
	v_mov_b32_e32 v3, v117
	v_lshl_add_u64 v[0:1], v[0:1], 0, v[2:3]
	v_lshlrev_b32_e32 v2, 1, v5
	v_lshl_add_u64 v[4:5], v[0:1], 0, v[2:3]
	ds_read_b128 v[0:3], v105 offset:49152
	s_mov_b32 s14, s35
	s_mov_b32 s0, s38
	s_waitcnt lgkmcnt(0)
	global_store_dwordx4 v[4:5], v[0:3], off
	s_waitcnt lgkmcnt(0)
	s_barrier
	s_cmp_eq_u32 s62, 2
	s_cbranch_scc0 .Lgu_eout
	s_mov_b32 s62, 0
	s_mov_b32 s38, s60
	s_mov_b32 s35, s61
	v_mov_b32_e32 v48, v150
	v_mov_b32_e32 v49, v151
	v_mov_b32_e32 v50, v152
	v_mov_b32_e32 v51, v153
	v_mov_b32_e32 v52, v154
	v_mov_b32_e32 v53, v155
	v_mov_b32_e32 v54, v156
	v_mov_b32_e32 v55, v157
	v_mov_b32_e32 v56, v158
	v_mov_b32_e32 v57, v159
	v_mov_b32_e32 v58, v160
	v_mov_b32_e32 v59, v161
	v_mov_b32_e32 v60, v162
	v_mov_b32_e32 v61, v163
	v_mov_b32_e32 v62, v164
	v_mov_b32_e32 v63, v165
	v_mov_b32_e32 v32, v166
	v_mov_b32_e32 v33, v167
	v_mov_b32_e32 v34, v168
	v_mov_b32_e32 v35, v169
	v_mov_b32_e32 v36, v170
	v_mov_b32_e32 v37, v171
	v_mov_b32_e32 v38, v172
	v_mov_b32_e32 v39, v173
	v_mov_b32_e32 v40, v174
	v_mov_b32_e32 v41, v175
	v_mov_b32_e32 v42, v176
	v_mov_b32_e32 v43, v177
	v_mov_b32_e32 v44, v178
	v_mov_b32_e32 v45, v179
	v_mov_b32_e32 v46, v180
	v_mov_b32_e32 v47, v181
	v_mov_b32_e32 v16, v184
	v_mov_b32_e32 v17, v185
	v_mov_b32_e32 v18, v186
	v_mov_b32_e32 v19, v187
	v_mov_b32_e32 v20, v188
	v_mov_b32_e32 v21, v189
	v_mov_b32_e32 v22, v190
	v_mov_b32_e32 v23, v191
	v_mov_b32_e32 v24, v192
	v_mov_b32_e32 v25, v193
	v_mov_b32_e32 v26, v194
	v_mov_b32_e32 v27, v195
	v_mov_b32_e32 v28, v196
	v_mov_b32_e32 v29, v197
	v_mov_b32_e32 v30, v198
	v_mov_b32_e32 v31, v199
	v_mov_b32_e32 v0, v226
	v_mov_b32_e32 v1, v227
	v_mov_b32_e32 v2, v228
	v_mov_b32_e32 v3, v229
	v_mov_b32_e32 v4, v230
	v_mov_b32_e32 v5, v231
	v_mov_b32_e32 v6, v232
	v_mov_b32_e32 v7, v233
	v_mov_b32_e32 v8, v234
	v_mov_b32_e32 v9, v235
	v_mov_b32_e32 v10, v236
	v_mov_b32_e32 v11, v237
	v_mov_b32_e32 v12, v238
	v_mov_b32_e32 v13, v239
	v_mov_b32_e32 v14, v240
	v_mov_b32_e32 v15, v241
	v_mov_b32_e32 v69, v201
	v_mov_b32_e32 v68, v200
	s_branch .LBB0_126
.Lgu_eout:
	s_cbranch_vccnz .LBB0_143

.LBB0_130:
	s_or_b64 exec, exec, s[20:21]
	s_add_i32 s1, s0, 0xfffff000
	s_lshr_b32 s1, s1, 10
	s_add_i32 s1, s1, 1
	s_cmpk_gt_i32 s0, 0xfff
	s_cselect_b32 s1, s1, 0
	s_mul_i32 s15, s12, 3
	s_add_i32 s1, s1, s15
	s_mul_hi_u32 s15, s1, 0xd000
	s_mul_i32 s1, s1, 0xd000
	s_add_u32 s1, s2, s1
	s_addc_u32 s39, s3, s15
	s_ashr_i32 s15, s14, 31
	s_lshl_b64 s[20:21], s[14:15], 2
	s_add_u32 s20, s1, s20
	s_addc_u32 s21, s39, s21
	v_lshl_add_u64 v[0:1], s[20:21], 0, v[116:117]
	v_mov_b32_e32 v87, v117
	v_lshl_add_u64 v[0:1], v[0:1], 0, v[86:87]
	s_mov_b64 s[20:21], 0x18e05800
	s_mov_b32 s1, 0x18e05000
	v_lshl_add_u64 v[2:3], v[0:1], 0, s[20:21]
	v_add_co_u32_e32 v0, vcc, s1, v0
	s_ashr_i32 s20, s0, 7
	s_nop 0
	v_addc_co_u32_e32 v1, vcc, 0, v1, vcc
	global_load_dword v69, v[0:1], off offset:2048
	global_load_dword v68, v[2:3], off offset:128
	global_load_dword v201, v[0:1], off offset:2560
	global_load_dword v200, v[2:3], off offset:640
	s_ashr_i32 s21, s20, 31
	s_lshl_b64 s[20:21], s[20:21], 18
	v_lshl_add_u64 v[64:65], v[80:81], 0, s[20:21]
	s_ashr_i32 s20, s14, 7
	s_ashr_i32 s21, s20, 31
	s_lshl_b64 s[20:21], s[20:21], 18
	v_lshl_add_u64 v[66:67], v[82:83], 0, s[20:21]
	s_mov_b64 s[20:21], -1
	s_andn2_b64 vcc, exec, s[18:19]
	v_add_u32_e32 v108, 0x400, v88
	v_add_u32_e32 v87, 0x2000, v88
	v_add_u32_e32 v79, 0x2400, v88
	v_add_u32_e32 v78, 0x4000, v88
	v_add_u32_e32 v77, 0x4400, v88
	v_add_u32_e32 v76, 0x6000, v88
	v_add_u32_e32 v75, 0x6400, v88
	v_add_u32_e32 v74, 0x8000, v88
	v_add_u32_e32 v73, 0x8400, v88
	v_add_u32_e32 v71, 0xa000, v88
	v_add_u32_e32 v70, 0xa400, v88
	s_cbranch_vccnz .LBB0_132
	v_readfirstlane_b32 s1, v88
	s_mov_b32 m0, s1
	s_mov_b64 s[18:19], 0x400
	v_readfirstlane_b32 s1, v108
	global_load_lds_dwordx4 v[64:65], off
	v_lshl_add_u64 v[0:1], v[64:65], 0, s[18:19]
	s_mov_b32 m0, s1
	v_readfirstlane_b32 s1, v87
	global_load_lds_dwordx4 v[0:1], off
	s_mov_b32 m0, s1
	v_readfirstlane_b32 s1, v79
	global_load_lds_dwordx4 v[66:67], off
	v_lshl_add_u64 v[0:1], v[66:67], 0, s[18:19]
	s_mov_b32 m0, s1
	v_readfirstlane_b32 s1, v78
	global_load_lds_dwordx4 v[0:1], off
	v_lshl_add_u64 v[0:1], v[64:65], 0, s[44:45]
	s_mov_b32 m0, s1
	v_readfirstlane_b32 s1, v77
	global_load_lds_dwordx4 v[0:1], off
	v_lshl_add_u64 v[0:1], v[64:65], 0, s[66:67]
	s_mov_b32 m0, s1
	v_readfirstlane_b32 s1, v76
	global_load_lds_dwordx4 v[0:1], off
	v_lshl_add_u64 v[0:1], v[66:67], 0, s[44:45]
	s_mov_b32 m0, s1
	v_readfirstlane_b32 s1, v75
	global_load_lds_dwordx4 v[0:1], off
	v_lshl_add_u64 v[0:1], v[66:67], 0, s[66:67]
	s_mov_b32 m0, s1
	v_readfirstlane_b32 s1, v74
	global_load_lds_dwordx4 v[0:1], off
	v_lshl_add_u64 v[0:1], v[64:65], 0, s[28:29]
	s_mov_b32 m0, s1
	s_mov_b64 s[18:19], 0x4400
	v_readfirstlane_b32 s1, v73
	global_load_lds_dwordx4 v[0:1], off
	v_lshl_add_u64 v[0:1], v[64:65], 0, s[18:19]
	s_mov_b32 m0, s1
	v_readfirstlane_b32 s1, v71
	global_load_lds_dwordx4 v[0:1], off
	v_lshl_add_u64 v[0:1], v[66:67], 0, s[28:29]
	s_mov_b32 m0, s1
	v_readfirstlane_b32 s1, v70
	global_load_lds_dwordx4 v[0:1], off
	v_lshl_add_u64 v[0:1], v[66:67], 0, s[18:19]
	s_mov_b32 m0, s1
	s_mov_b64 s[20:21], 0
	global_load_lds_dwordx4 v[0:1], off
	s_waitcnt vmcnt(8)

.LBB0_134:
	s_cmp_lt_u32 s63, 2
	s_cbranch_scc1 .Lgu_pair
	s_mov_b32 s62, 0
	s_branch .Lgu_single
.Lgu_pair:
	s_add_i32 s63, s63, 1
	s_mov_b32 s62, 1
	v_add_u32_e32 v109, v89, v91
	v_add_u32_e32 v114, v90, v91
	v_add_u32_e32 v115, v89, v92
	v_add_u32_e32 v119, v90, v92
	v_add_u32_e32 v121, 0x4000, v114
	v_add_u32_e32 v122, 0x4000, v119
	v_readfirstlane_b32 s50, v88
	s_mov_b64 s[72:73], 0x40000
	s_mov_b64 s[86:87], 0x4000
	s_add_u32 s51, s50, 0x4000
	s_add_u32 s52, s50, 0x8000
	s_add_u32 s53, s50, 0x2000
	s_add_u32 s54, s50, 0x6000
	s_add_u32 s55, s50, 0xa000
	s_add_u32 s56, s50, 0xc000
	s_add_u32 s57, s50, 0xe000
	s_add_u32 s58, s50, 0x12000
	v_lshl_add_u64 v[148:149], v[66:67], 0, s[72:73]
	s_mov_b32 m0, s56
	s_nop 0
	global_load_lds_dwordx4 v[148:149], off
	global_load_lds_dwordx4 v[148:149], off offset:1024
	v_lshl_add_u64 v[148:149], v[148:149], 0, s[44:45]
	s_mov_b32 m0, s57
	s_nop 0
	global_load_lds_dwordx4 v[148:149], off
	global_load_lds_dwordx4 v[148:149], off offset:1024
	v_lshl_add_u64 v[148:149], v[148:149], 0, s[44:45]
	s_mov_b32 m0, s58
	s_nop 0
	global_load_lds_dwordx4 v[148:149], off
	global_load_lds_dwordx4 v[148:149], off offset:1024
	v_lshl_add_u64 v[64:65], v[64:65], 0, s[86:87]
	v_lshl_add_u64 v[66:67], v[66:67], 0, s[86:87]
	s_waitcnt vmcnt(4)
	s_waitcnt lgkmcnt(0)
	s_barrier
	ds_read_b128 v[110:113], v109
	ds_read_b128 v[132:135], v114 offset:8192
	ds_read_b128 v[136:139], v114 offset:10240
	ds_read_b128 v[140:143], v114 offset:49152
	ds_read_b128 v[144:147], v114 offset:51200
	ds_read_b128 v[128:131], v109 offset:2048
	ds_read_b128 v[202:205], v115
	ds_read_b128 v[214:217], v119 offset:8192
	ds_read_b128 v[244:247], v119 offset:10240
	ds_read_b128 v[250:253], v119 offset:49152
	ds_read_b128 v[206:209], v115 offset:2048
	ds_read_b128 v[74:77], v119 offset:51200
	s_waitcnt lgkmcnt(6)
	v_mfma_f32_32x32x16_bf16 v[48:63], v[110:113], v[132:135], 0
	v_mfma_f32_32x32x16_bf16 v[32:47], v[110:113], v[136:139], 0
	v_mfma_f32_32x32x16_bf16 v[150:165], v[110:113], v[140:143], 0
	v_mfma_f32_32x32x16_bf16 v[166:181], v[110:113], v[144:147], 0
	v_mfma_f32_32x32x16_bf16 v[16:31], v[128:131], v[132:135], 0
	v_mfma_f32_32x32x16_bf16 v[0:15], v[128:131], v[136:139], 0
	v_mfma_f32_32x32x16_bf16 v[184:199], v[128:131], v[140:143], 0
	v_mfma_f32_32x32x16_bf16 v[226:241], v[128:131], v[144:147], 0
	s_waitcnt vmcnt(2)
	s_waitcnt lgkmcnt(0)
	s_barrier
	ds_read_b128 v[110:113], v109 offset:16384
	ds_read_b128 v[132:135], v114 offset:24576
	v_mfma_f32_32x32x16_bf16 v[48:63], v[202:205], v[214:217], v[48:63]
	ds_read_b128 v[136:139], v114 offset:26624
	ds_read_b128 v[140:143], v121 offset:40960
	v_mfma_f32_32x32x16_bf16 v[32:47], v[202:205], v[244:247], v[32:47]
	ds_read_b128 v[144:147], v121 offset:43008
	ds_read_b128 v[128:131], v109 offset:18432
	v_mfma_f32_32x32x16_bf16 v[150:165], v[202:205], v[250:253], v[150:165]
	s_mov_b32 m0, s50
	v_lshl_add_u64 v[64:65], v[64:65], 0, s[44:45]
	global_load_lds_dwordx4 v[64:65], off
	global_load_lds_dwordx4 v[64:65], off offset:1024
	v_mfma_f32_32x32x16_bf16 v[166:181], v[202:205], v[74:77], v[166:181]
	ds_read_b128 v[202:205], v115 offset:16384
	s_mov_b32 m0, s53
	v_lshl_add_u64 v[66:67], v[66:67], 0, s[44:45]
	global_load_lds_dwordx4 v[66:67], off
	global_load_lds_dwordx4 v[66:67], off offset:1024
	v_mfma_f32_32x32x16_bf16 v[16:31], v[206:209], v[214:217], v[16:31]
	ds_read_b128 v[214:217], v119 offset:24576
	s_mov_b32 m0, s56
	v_lshl_add_u64 v[148:149], v[66:67], 0, s[72:73]
	global_load_lds_dwordx4 v[148:149], off
	global_load_lds_dwordx4 v[148:149], off offset:1024
	v_mfma_f32_32x32x16_bf16 v[0:15], v[206:209], v[244:247], v[0:15]
	ds_read_b128 v[244:247], v119 offset:26624
	v_mfma_f32_32x32x16_bf16 v[184:199], v[206:209], v[250:253], v[184:199]
	ds_read_b128 v[250:253], v122 offset:40960
	v_mfma_f32_32x32x16_bf16 v[226:241], v[206:209], v[74:77], v[226:241]
	ds_read_b128 v[206:209], v115 offset:18432
	ds_read_b128 v[74:77], v122 offset:43008
	s_waitcnt lgkmcnt(6)
	v_mfma_f32_32x32x16_bf16 v[48:63], v[110:113], v[132:135], v[48:63]
	v_mfma_f32_32x32x16_bf16 v[32:47], v[110:113], v[136:139], v[32:47]
	v_mfma_f32_32x32x16_bf16 v[150:165], v[110:113], v[140:143], v[150:165]
	v_mfma_f32_32x32x16_bf16 v[166:181], v[110:113], v[144:147], v[166:181]
	v_mfma_f32_32x32x16_bf16 v[16:31], v[128:131], v[132:135], v[16:31]
	v_mfma_f32_32x32x16_bf16 v[0:15], v[128:131], v[136:139], v[0:15]
	v_mfma_f32_32x32x16_bf16 v[184:199], v[128:131], v[140:143], v[184:199]
	v_mfma_f32_32x32x16_bf16 v[226:241], v[128:131], v[144:147], v[226:241]
	s_waitcnt vmcnt(6)
	s_waitcnt lgkmcnt(0)
	s_barrier
	ds_read_b128 v[110:113], v109 offset:32768
	ds_read_b128 v[132:135], v114 offset:40960
	v_mfma_f32_32x32x16_bf16 v[48:63], v[202:205], v[214:217], v[48:63]
	ds_read_b128 v[136:139], v114 offset:43008
	ds_read_b128 v[140:143], v121 offset:57344
	v_mfma_f32_32x32x16_bf16 v[32:47], v[202:205], v[244:247], v[32:47]
	ds_read_b128 v[144:147], v121 offset:59392
	ds_read_b128 v[128:131], v109 offset:34816
	v_mfma_f32_32x32x16_bf16 v[150:165], v[202:205], v[250:253], v[150:165]
	s_mov_b32 m0, s51
	v_lshl_add_u64 v[64:65], v[64:65], 0, s[44:45]
	global_load_lds_dwordx4 v[64:65], off
	global_load_lds_dwordx4 v[64:65], off offset:1024
	v_mfma_f32_32x32x16_bf16 v[166:181], v[202:205], v[74:77], v[166:181]
	ds_read_b128 v[202:205], v115 offset:32768
	s_mov_b32 m0, s54
	v_lshl_add_u64 v[66:67], v[66:67], 0, s[44:45]
	global_load_lds_dwordx4 v[66:67], off
	global_load_lds_dwordx4 v[66:67], off offset:1024
	v_mfma_f32_32x32x16_bf16 v[16:31], v[206:209], v[214:217], v[16:31]
	ds_read_b128 v[214:217], v119 offset:40960
	s_mov_b32 m0, s57
	v_lshl_add_u64 v[148:149], v[66:67], 0, s[72:73]
	global_load_lds_dwordx4 v[148:149], off
	global_load_lds_dwordx4 v[148:149], off offset:1024
	v_mfma_f32_32x32x16_bf16 v[0:15], v[206:209], v[244:247], v[0:15]
	ds_read_b128 v[244:247], v119 offset:43008
	v_mfma_f32_32x32x16_bf16 v[184:199], v[206:209], v[250:253], v[184:199]
	ds_read_b128 v[250:253], v122 offset:57344
	v_mfma_f32_32x32x16_bf16 v[226:241], v[206:209], v[74:77], v[226:241]
	ds_read_b128 v[206:209], v115 offset:34816
	ds_read_b128 v[74:77], v122 offset:59392
	s_waitcnt lgkmcnt(6)
	v_mfma_f32_32x32x16_bf16 v[48:63], v[110:113], v[132:135], v[48:63]
	v_mfma_f32_32x32x16_bf16 v[32:47], v[110:113], v[136:139], v[32:47]
	v_mfma_f32_32x32x16_bf16 v[150:165], v[110:113], v[140:143], v[150:165]
	v_mfma_f32_32x32x16_bf16 v[166:181], v[110:113], v[144:147], v[166:181]
	v_mfma_f32_32x32x16_bf16 v[16:31], v[128:131], v[132:135], v[16:31]
	v_mfma_f32_32x32x16_bf16 v[0:15], v[128:131], v[136:139], v[0:15]
	v_mfma_f32_32x32x16_bf16 v[184:199], v[128:131], v[140:143], v[184:199]
	v_mfma_f32_32x32x16_bf16 v[226:241], v[128:131], v[144:147], v[226:241]
	s_waitcnt vmcnt(6)
	s_waitcnt lgkmcnt(0)
	s_barrier
	ds_read_b128 v[110:113], v109
	ds_read_b128 v[132:135], v114 offset:8192
	v_mfma_f32_32x32x16_bf16 v[48:63], v[202:205], v[214:217], v[48:63]
	ds_read_b128 v[136:139], v114 offset:10240
	ds_read_b128 v[140:143], v114 offset:49152
	v_mfma_f32_32x32x16_bf16 v[32:47], v[202:205], v[244:247], v[32:47]
	ds_read_b128 v[144:147], v114 offset:51200
	ds_read_b128 v[128:131], v109 offset:2048
	v_mfma_f32_32x32x16_bf16 v[150:165], v[202:205], v[250:253], v[150:165]
	s_mov_b32 m0, s52
	v_lshl_add_u64 v[64:65], v[64:65], 0, s[44:45]
	global_load_lds_dwordx4 v[64:65], off
	global_load_lds_dwordx4 v[64:65], off offset:1024
	v_mfma_f32_32x32x16_bf16 v[166:181], v[202:205], v[74:77], v[166:181]
	ds_read_b128 v[202:205], v115
	s_mov_b32 m0, s55
	v_lshl_add_u64 v[66:67], v[66:67], 0, s[44:45]
	global_load_lds_dwordx4 v[66:67], off
	global_load_lds_dwordx4 v[66:67], off offset:1024
	v_mfma_f32_32x32x16_bf16 v[16:31], v[206:209], v[214:217], v[16:31]
	ds_read_b128 v[214:217], v119 offset:8192
	s_mov_b32 m0, s58
	v_lshl_add_u64 v[148:149], v[66:67], 0, s[72:73]
	global_load_lds_dwordx4 v[148:149], off
	global_load_lds_dwordx4 v[148:149], off offset:1024
	v_mfma_f32_32x32x16_bf16 v[0:15], v[206:209], v[244:247], v[0:15]
	ds_read_b128 v[244:247], v119 offset:10240
	v_mfma_f32_32x32x16_bf16 v[184:199], v[206:209], v[250:253], v[184:199]
	ds_read_b128 v[250:253], v119 offset:49152
	v_mfma_f32_32x32x16_bf16 v[226:241], v[206:209], v[74:77], v[226:241]
	ds_read_b128 v[206:209], v115 offset:2048
	ds_read_b128 v[74:77], v119 offset:51200
	s_waitcnt lgkmcnt(6)
	v_mfma_f32_32x32x16_bf16 v[48:63], v[110:113], v[132:135], v[48:63]
	v_mfma_f32_32x32x16_bf16 v[32:47], v[110:113], v[136:139], v[32:47]
	v_mfma_f32_32x32x16_bf16 v[150:165], v[110:113], v[140:143], v[150:165]
	v_mfma_f32_32x32x16_bf16 v[166:181], v[110:113], v[144:147], v[166:181]
	v_mfma_f32_32x32x16_bf16 v[16:31], v[128:131], v[132:135], v[16:31]
	v_mfma_f32_32x32x16_bf16 v[0:15], v[128:131], v[136:139], v[0:15]
	v_mfma_f32_32x32x16_bf16 v[184:199], v[128:131], v[140:143], v[184:199]
	v_mfma_f32_32x32x16_bf16 v[226:241], v[128:131], v[144:147], v[226:241]
	s_waitcnt vmcnt(6)
	s_waitcnt lgkmcnt(0)
	s_barrier
	ds_read_b128 v[110:113], v109 offset:16384
	ds_read_b128 v[132:135], v114 offset:24576
	v_mfma_f32_32x32x16_bf16 v[48:63], v[202:205], v[214:217], v[48:63]
	ds_read_b128 v[136:139], v114 offset:26624
	ds_read_b128 v[140:143], v121 offset:40960
	v_mfma_f32_32x32x16_bf16 v[32:47], v[202:205], v[244:247], v[32:47]
	ds_read_b128 v[144:147], v121 offset:43008
	ds_read_b128 v[128:131], v109 offset:18432
	v_mfma_f32_32x32x16_bf16 v[150:165], v[202:205], v[250:253], v[150:165]
	s_mov_b32 m0, s50
	v_lshl_add_u64 v[64:65], v[64:65], 0, s[44:45]
	global_load_lds_dwordx4 v[64:65], off
	global_load_lds_dwordx4 v[64:65], off offset:1024
	v_mfma_f32_32x32x16_bf16 v[166:181], v[202:205], v[74:77], v[166:181]
	ds_read_b128 v[202:205], v115 offset:16384
	s_mov_b32 m0, s53
	v_lshl_add_u64 v[66:67], v[66:67], 0, s[44:45]
	global_load_lds_dwordx4 v[66:67], off
	global_load_lds_dwordx4 v[66:67], off offset:1024
	v_mfma_f32_32x32x16_bf16 v[16:31], v[206:209], v[214:217], v[16:31]
	ds_read_b128 v[214:217], v119 offset:24576
	s_mov_b32 m0, s56
	v_lshl_add_u64 v[148:149], v[66:67], 0, s[72:73]
	global_load_lds_dwordx4 v[148:149], off
	global_load_lds_dwordx4 v[148:149], off offset:1024
	v_mfma_f32_32x32x16_bf16 v[0:15], v[206:209], v[244:247], v[0:15]
	ds_read_b128 v[244:247], v119 offset:26624
	v_mfma_f32_32x32x16_bf16 v[184:199], v[206:209], v[250:253], v[184:199]
	ds_read_b128 v[250:253], v122 offset:40960
	v_mfma_f32_32x32x16_bf16 v[226:241], v[206:209], v[74:77], v[226:241]
	ds_read_b128 v[206:209], v115 offset:18432
	ds_read_b128 v[74:77], v122 offset:43008
	s_waitcnt lgkmcnt(6)
	v_mfma_f32_32x32x16_bf16 v[48:63], v[110:113], v[132:135], v[48:63]
	v_mfma_f32_32x32x16_bf16 v[32:47], v[110:113], v[136:139], v[32:47]
	v_mfma_f32_32x32x16_bf16 v[150:165], v[110:113], v[140:143], v[150:165]
	v_mfma_f32_32x32x16_bf16 v[166:181], v[110:113], v[144:147], v[166:181]
	v_mfma_f32_32x32x16_bf16 v[16:31], v[128:131], v[132:135], v[16:31]
	v_mfma_f32_32x32x16_bf16 v[0:15], v[128:131], v[136:139], v[0:15]
	v_mfma_f32_32x32x16_bf16 v[184:199], v[128:131], v[140:143], v[184:199]
	v_mfma_f32_32x32x16_bf16 v[226:241], v[128:131], v[144:147], v[226:241]
	s_waitcnt vmcnt(6)
	s_waitcnt lgkmcnt(0)
	s_barrier
	ds_read_b128 v[110:113], v109 offset:32768
	ds_read_b128 v[132:135], v114 offset:40960
	v_mfma_f32_32x32x16_bf16 v[48:63], v[202:205], v[214:217], v[48:63]
	ds_read_b128 v[136:139], v114 offset:43008
	ds_read_b128 v[140:143], v121 offset:57344
	v_mfma_f32_32x32x16_bf16 v[32:47], v[202:205], v[244:247], v[32:47]
	ds_read_b128 v[144:147], v121 offset:59392
	ds_read_b128 v[128:131], v109 offset:34816
	v_mfma_f32_32x32x16_bf16 v[150:165], v[202:205], v[250:253], v[150:165]
	s_mov_b32 m0, s51
	v_lshl_add_u64 v[64:65], v[64:65], 0, s[44:45]
	global_load_lds_dwordx4 v[64:65], off
	global_load_lds_dwordx4 v[64:65], off offset:1024
	v_mfma_f32_32x32x16_bf16 v[166:181], v[202:205], v[74:77], v[166:181]
	ds_read_b128 v[202:205], v115 offset:32768
	s_mov_b32 m0, s54
	v_lshl_add_u64 v[66:67], v[66:67], 0, s[44:45]
	global_load_lds_dwordx4 v[66:67], off
	global_load_lds_dwordx4 v[66:67], off offset:1024
	v_mfma_f32_32x32x16_bf16 v[16:31], v[206:209], v[214:217], v[16:31]
	ds_read_b128 v[214:217], v119 offset:40960
	s_mov_b32 m0, s57
	v_lshl_add_u64 v[148:149], v[66:67], 0, s[72:73]
	global_load_lds_dwordx4 v[148:149], off
	global_load_lds_dwordx4 v[148:149], off offset:1024
	v_mfma_f32_32x32x16_bf16 v[0:15], v[206:209], v[244:247], v[0:15]
	ds_read_b128 v[244:247], v119 offset:43008
	v_mfma_f32_32x32x16_bf16 v[184:199], v[206:209], v[250:253], v[184:199]
	ds_read_b128 v[250:253], v122 offset:57344
	v_mfma_f32_32x32x16_bf16 v[226:241], v[206:209], v[74:77], v[226:241]
	ds_read_b128 v[206:209], v115 offset:34816
	ds_read_b128 v[74:77], v122 offset:59392
	s_waitcnt lgkmcnt(6)
	v_mfma_f32_32x32x16_bf16 v[48:63], v[110:113], v[132:135], v[48:63]
	v_mfma_f32_32x32x16_bf16 v[32:47], v[110:113], v[136:139], v[32:47]
	v_mfma_f32_32x32x16_bf16 v[150:165], v[110:113], v[140:143], v[150:165]
	v_mfma_f32_32x32x16_bf16 v[166:181], v[110:113], v[144:147], v[166:181]
	v_mfma_f32_32x32x16_bf16 v[16:31], v[128:131], v[132:135], v[16:31]
	v_mfma_f32_32x32x16_bf16 v[0:15], v[128:131], v[136:139], v[0:15]
	v_mfma_f32_32x32x16_bf16 v[184:199], v[128:131], v[140:143], v[184:199]
	v_mfma_f32_32x32x16_bf16 v[226:241], v[128:131], v[144:147], v[226:241]
	s_waitcnt vmcnt(6)
	s_waitcnt lgkmcnt(0)
	s_barrier
	ds_read_b128 v[110:113], v109
	ds_read_b128 v[132:135], v114 offset:8192
	v_mfma_f32_32x32x16_bf16 v[48:63], v[202:205], v[214:217], v[48:63]
	ds_read_b128 v[136:139], v114 offset:10240
	ds_read_b128 v[140:143], v114 offset:49152
	v_mfma_f32_32x32x16_bf16 v[32:47], v[202:205], v[244:247], v[32:47]
	ds_read_b128 v[144:147], v114 offset:51200
	ds_read_b128 v[128:131], v109 offset:2048
	v_mfma_f32_32x32x16_bf16 v[150:165], v[202:205], v[250:253], v[150:165]
	s_mov_b32 m0, s52
	v_lshl_add_u64 v[64:65], v[64:65], 0, s[44:45]
	global_load_lds_dwordx4 v[64:65], off
	global_load_lds_dwordx4 v[64:65], off offset:1024
	v_mfma_f32_32x32x16_bf16 v[166:181], v[202:205], v[74:77], v[166:181]
	ds_read_b128 v[202:205], v115
	s_mov_b32 m0, s55
	v_lshl_add_u64 v[66:67], v[66:67], 0, s[44:45]
	global_load_lds_dwordx4 v[66:67], off
	global_load_lds_dwordx4 v[66:67], off offset:1024
	v_mfma_f32_32x32x16_bf16 v[16:31], v[206:209], v[214:217], v[16:31]
	ds_read_b128 v[214:217], v119 offset:8192
	s_mov_b32 m0, s58
	v_lshl_add_u64 v[148:149], v[66:67], 0, s[72:73]
	global_load_lds_dwordx4 v[148:149], off
	global_load_lds_dwordx4 v[148:149], off offset:1024
	v_mfma_f32_32x32x16_bf16 v[0:15], v[206:209], v[244:247], v[0:15]
	ds_read_b128 v[244:247], v119 offset:10240
	v_mfma_f32_32x32x16_bf16 v[184:199], v[206:209], v[250:253], v[184:199]
	ds_read_b128 v[250:253], v119 offset:49152
	v_mfma_f32_32x32x16_bf16 v[226:241], v[206:209], v[74:77], v[226:241]
	ds_read_b128 v[206:209], v115 offset:2048
	ds_read_b128 v[74:77], v119 offset:51200
	s_waitcnt lgkmcnt(6)
	v_mfma_f32_32x32x16_bf16 v[48:63], v[110:113], v[132:135], v[48:63]
	v_mfma_f32_32x32x16_bf16 v[32:47], v[110:113], v[136:139], v[32:47]
	v_mfma_f32_32x32x16_bf16 v[150:165], v[110:113], v[140:143], v[150:165]
	v_mfma_f32_32x32x16_bf16 v[166:181], v[110:113], v[144:147], v[166:181]
	v_mfma_f32_32x32x16_bf16 v[16:31], v[128:131], v[132:135], v[16:31]
	v_mfma_f32_32x32x16_bf16 v[0:15], v[128:131], v[136:139], v[0:15]
	v_mfma_f32_32x32x16_bf16 v[184:199], v[128:131], v[140:143], v[184:199]
	v_mfma_f32_32x32x16_bf16 v[226:241], v[128:131], v[144:147], v[226:241]
	s_waitcnt vmcnt(6)
	s_waitcnt lgkmcnt(0)
	s_barrier
	ds_read_b128 v[110:113], v109 offset:16384
	ds_read_b128 v[132:135], v114 offset:24576
	v_mfma_f32_32x32x16_bf16 v[48:63], v[202:205], v[214:217], v[48:63]
	ds_read_b128 v[136:139], v114 offset:26624
	ds_read_b128 v[140:143], v121 offset:40960
	v_mfma_f32_32x32x16_bf16 v[32:47], v[202:205], v[244:247], v[32:47]
	ds_read_b128 v[144:147], v121 offset:43008
	ds_read_b128 v[128:131], v109 offset:18432
	v_mfma_f32_32x32x16_bf16 v[150:165], v[202:205], v[250:253], v[150:165]
	s_mov_b32 m0, s50
	v_lshl_add_u64 v[64:65], v[64:65], 0, s[44:45]
	global_load_lds_dwordx4 v[64:65], off
	global_load_lds_dwordx4 v[64:65], off offset:1024
	v_mfma_f32_32x32x16_bf16 v[166:181], v[202:205], v[74:77], v[166:181]
	ds_read_b128 v[202:205], v115 offset:16384
	s_mov_b32 m0, s53
	v_lshl_add_u64 v[66:67], v[66:67], 0, s[44:45]
	global_load_lds_dwordx4 v[66:67], off
	global_load_lds_dwordx4 v[66:67], off offset:1024
	v_mfma_f32_32x32x16_bf16 v[16:31], v[206:209], v[214:217], v[16:31]
	ds_read_b128 v[214:217], v119 offset:24576
	s_mov_b32 m0, s56
	v_lshl_add_u64 v[148:149], v[66:67], 0, s[72:73]
	global_load_lds_dwordx4 v[148:149], off
	global_load_lds_dwordx4 v[148:149], off offset:1024
	v_mfma_f32_32x32x16_bf16 v[0:15], v[206:209], v[244:247], v[0:15]
	ds_read_b128 v[244:247], v119 offset:26624
	v_mfma_f32_32x32x16_bf16 v[184:199], v[206:209], v[250:253], v[184:199]
	ds_read_b128 v[250:253], v122 offset:40960
	v_mfma_f32_32x32x16_bf16 v[226:241], v[206:209], v[74:77], v[226:241]
	ds_read_b128 v[206:209], v115 offset:18432
	ds_read_b128 v[74:77], v122 offset:43008
	s_waitcnt lgkmcnt(6)
	v_mfma_f32_32x32x16_bf16 v[48:63], v[110:113], v[132:135], v[48:63]
	v_mfma_f32_32x32x16_bf16 v[32:47], v[110:113], v[136:139], v[32:47]
	v_mfma_f32_32x32x16_bf16 v[150:165], v[110:113], v[140:143], v[150:165]
	v_mfma_f32_32x32x16_bf16 v[166:181], v[110:113], v[144:147], v[166:181]
	v_mfma_f32_32x32x16_bf16 v[16:31], v[128:131], v[132:135], v[16:31]
	v_mfma_f32_32x32x16_bf16 v[0:15], v[128:131], v[136:139], v[0:15]
	v_mfma_f32_32x32x16_bf16 v[184:199], v[128:131], v[140:143], v[184:199]
	v_mfma_f32_32x32x16_bf16 v[226:241], v[128:131], v[144:147], v[226:241]
	s_waitcnt vmcnt(6)
	s_waitcnt lgkmcnt(0)
	s_barrier
	ds_read_b128 v[110:113], v109 offset:32768
	ds_read_b128 v[132:135], v114 offset:40960
	v_mfma_f32_32x32x16_bf16 v[48:63], v[202:205], v[214:217], v[48:63]
	ds_read_b128 v[136:139], v114 offset:43008
	ds_read_b128 v[140:143], v121 offset:57344
	v_mfma_f32_32x32x16_bf16 v[32:47], v[202:205], v[244:247], v[32:47]
	ds_read_b128 v[144:147], v121 offset:59392
	ds_read_b128 v[128:131], v109 offset:34816
	v_mfma_f32_32x32x16_bf16 v[150:165], v[202:205], v[250:253], v[150:165]
	s_mov_b32 m0, s51
	v_lshl_add_u64 v[64:65], v[64:65], 0, s[44:45]
	global_load_lds_dwordx4 v[64:65], off
	global_load_lds_dwordx4 v[64:65], off offset:1024
	v_mfma_f32_32x32x16_bf16 v[166:181], v[202:205], v[74:77], v[166:181]
	ds_read_b128 v[202:205], v115 offset:32768
	s_mov_b32 m0, s54
	v_lshl_add_u64 v[66:67], v[66:67], 0, s[44:45]
	global_load_lds_dwordx4 v[66:67], off
	global_load_lds_dwordx4 v[66:67], off offset:1024
	v_mfma_f32_32x32x16_bf16 v[16:31], v[206:209], v[214:217], v[16:31]
	ds_read_b128 v[214:217], v119 offset:40960
	s_mov_b32 m0, s57
	v_lshl_add_u64 v[148:149], v[66:67], 0, s[72:73]
	global_load_lds_dwordx4 v[148:149], off
	global_load_lds_dwordx4 v[148:149], off offset:1024
	v_mfma_f32_32x32x16_bf16 v[0:15], v[206:209], v[244:247], v[0:15]
	ds_read_b128 v[244:247], v119 offset:43008
	v_mfma_f32_32x32x16_bf16 v[184:199], v[206:209], v[250:253], v[184:199]
	ds_read_b128 v[250:253], v122 offset:57344
	v_mfma_f32_32x32x16_bf16 v[226:241], v[206:209], v[74:77], v[226:241]
	ds_read_b128 v[206:209], v115 offset:34816
	ds_read_b128 v[74:77], v122 offset:59392
	s_waitcnt lgkmcnt(6)
	v_mfma_f32_32x32x16_bf16 v[48:63], v[110:113], v[132:135], v[48:63]
	v_mfma_f32_32x32x16_bf16 v[32:47], v[110:113], v[136:139], v[32:47]
	v_mfma_f32_32x32x16_bf16 v[150:165], v[110:113], v[140:143], v[150:165]
	v_mfma_f32_32x32x16_bf16 v[166:181], v[110:113], v[144:147], v[166:181]
	v_mfma_f32_32x32x16_bf16 v[16:31], v[128:131], v[132:135], v[16:31]
	v_mfma_f32_32x32x16_bf16 v[0:15], v[128:131], v[136:139], v[0:15]
	v_mfma_f32_32x32x16_bf16 v[184:199], v[128:131], v[140:143], v[184:199]
	v_mfma_f32_32x32x16_bf16 v[226:241], v[128:131], v[144:147], v[226:241]
	s_waitcnt vmcnt(6)
	s_waitcnt lgkmcnt(0)
	s_barrier
	ds_read_b128 v[110:113], v109
	ds_read_b128 v[132:135], v114 offset:8192
	v_mfma_f32_32x32x16_bf16 v[48:63], v[202:205], v[214:217], v[48:63]
	ds_read_b128 v[136:139], v114 offset:10240
	ds_read_b128 v[140:143], v114 offset:49152
	v_mfma_f32_32x32x16_bf16 v[32:47], v[202:205], v[244:247], v[32:47]
	ds_read_b128 v[144:147], v114 offset:51200
	ds_read_b128 v[128:131], v109 offset:2048
	v_mfma_f32_32x32x16_bf16 v[150:165], v[202:205], v[250:253], v[150:165]
	s_mov_b32 m0, s52
	v_lshl_add_u64 v[64:65], v[64:65], 0, s[44:45]
	global_load_lds_dwordx4 v[64:65], off
	global_load_lds_dwordx4 v[64:65], off offset:1024
	v_mfma_f32_32x32x16_bf16 v[166:181], v[202:205], v[74:77], v[166:181]
	ds_read_b128 v[202:205], v115
	s_mov_b32 m0, s55
	v_lshl_add_u64 v[66:67], v[66:67], 0, s[44:45]
	global_load_lds_dwordx4 v[66:67], off
	global_load_lds_dwordx4 v[66:67], off offset:1024
	v_mfma_f32_32x32x16_bf16 v[16:31], v[206:209], v[214:217], v[16:31]
	ds_read_b128 v[214:217], v119 offset:8192
	s_mov_b32 m0, s58
	v_lshl_add_u64 v[148:149], v[66:67], 0, s[72:73]
	global_load_lds_dwordx4 v[148:149], off
	global_load_lds_dwordx4 v[148:149], off offset:1024
	v_mfma_f32_32x32x16_bf16 v[0:15], v[206:209], v[244:247], v[0:15]
	ds_read_b128 v[244:247], v119 offset:10240
	v_mfma_f32_32x32x16_bf16 v[184:199], v[206:209], v[250:253], v[184:199]
	ds_read_b128 v[250:253], v119 offset:49152
	v_mfma_f32_32x32x16_bf16 v[226:241], v[206:209], v[74:77], v[226:241]
	ds_read_b128 v[206:209], v115 offset:2048
	ds_read_b128 v[74:77], v119 offset:51200
	s_waitcnt lgkmcnt(6)
	v_mfma_f32_32x32x16_bf16 v[48:63], v[110:113], v[132:135], v[48:63]
	v_mfma_f32_32x32x16_bf16 v[32:47], v[110:113], v[136:139], v[32:47]
	v_mfma_f32_32x32x16_bf16 v[150:165], v[110:113], v[140:143], v[150:165]
	v_mfma_f32_32x32x16_bf16 v[166:181], v[110:113], v[144:147], v[166:181]
	v_mfma_f32_32x32x16_bf16 v[16:31], v[128:131], v[132:135], v[16:31]
	v_mfma_f32_32x32x16_bf16 v[0:15], v[128:131], v[136:139], v[0:15]
	v_mfma_f32_32x32x16_bf16 v[184:199], v[128:131], v[140:143], v[184:199]
	v_mfma_f32_32x32x16_bf16 v[226:241], v[128:131], v[144:147], v[226:241]
	s_waitcnt vmcnt(6)
	s_waitcnt lgkmcnt(0)
	s_barrier
	ds_read_b128 v[110:113], v109 offset:16384
	ds_read_b128 v[132:135], v114 offset:24576
	v_mfma_f32_32x32x16_bf16 v[48:63], v[202:205], v[214:217], v[48:63]
	ds_read_b128 v[136:139], v114 offset:26624
	ds_read_b128 v[140:143], v121 offset:40960
	v_mfma_f32_32x32x16_bf16 v[32:47], v[202:205], v[244:247], v[32:47]
	ds_read_b128 v[144:147], v121 offset:43008
	ds_read_b128 v[128:131], v109 offset:18432
	v_mfma_f32_32x32x16_bf16 v[150:165], v[202:205], v[250:253], v[150:165]
	s_mov_b32 m0, s50
	v_lshl_add_u64 v[64:65], v[64:65], 0, s[44:45]
	global_load_lds_dwordx4 v[64:65], off
	global_load_lds_dwordx4 v[64:65], off offset:1024
	v_mfma_f32_32x32x16_bf16 v[166:181], v[202:205], v[74:77], v[166:181]
	ds_read_b128 v[202:205], v115 offset:16384
	s_mov_b32 m0, s53
	v_lshl_add_u64 v[66:67], v[66:67], 0, s[44:45]
	global_load_lds_dwordx4 v[66:67], off
	global_load_lds_dwordx4 v[66:67], off offset:1024
	v_mfma_f32_32x32x16_bf16 v[16:31], v[206:209], v[214:217], v[16:31]
	ds_read_b128 v[214:217], v119 offset:24576
	s_mov_b32 m0, s56
	v_lshl_add_u64 v[148:149], v[66:67], 0, s[72:73]
	global_load_lds_dwordx4 v[148:149], off
	global_load_lds_dwordx4 v[148:149], off offset:1024
	v_mfma_f32_32x32x16_bf16 v[0:15], v[206:209], v[244:247], v[0:15]
	ds_read_b128 v[244:247], v119 offset:26624
	v_mfma_f32_32x32x16_bf16 v[184:199], v[206:209], v[250:253], v[184:199]
	ds_read_b128 v[250:253], v122 offset:40960
	v_mfma_f32_32x32x16_bf16 v[226:241], v[206:209], v[74:77], v[226:241]
	ds_read_b128 v[206:209], v115 offset:18432
	ds_read_b128 v[74:77], v122 offset:43008
	s_waitcnt lgkmcnt(6)
	v_mfma_f32_32x32x16_bf16 v[48:63], v[110:113], v[132:135], v[48:63]
	v_mfma_f32_32x32x16_bf16 v[32:47], v[110:113], v[136:139], v[32:47]
	v_mfma_f32_32x32x16_bf16 v[150:165], v[110:113], v[140:143], v[150:165]
	v_mfma_f32_32x32x16_bf16 v[166:181], v[110:113], v[144:147], v[166:181]
	v_mfma_f32_32x32x16_bf16 v[16:31], v[128:131], v[132:135], v[16:31]
	v_mfma_f32_32x32x16_bf16 v[0:15], v[128:131], v[136:139], v[0:15]
	v_mfma_f32_32x32x16_bf16 v[184:199], v[128:131], v[140:143], v[184:199]
	v_mfma_f32_32x32x16_bf16 v[226:241], v[128:131], v[144:147], v[226:241]
	s_waitcnt vmcnt(6)
	s_waitcnt lgkmcnt(0)
	s_barrier
	ds_read_b128 v[110:113], v109 offset:32768
	ds_read_b128 v[132:135], v114 offset:40960
	v_mfma_f32_32x32x16_bf16 v[48:63], v[202:205], v[214:217], v[48:63]
	ds_read_b128 v[136:139], v114 offset:43008
	ds_read_b128 v[140:143], v121 offset:57344
	v_mfma_f32_32x32x16_bf16 v[32:47], v[202:205], v[244:247], v[32:47]
	ds_read_b128 v[144:147], v121 offset:59392
	ds_read_b128 v[128:131], v109 offset:34816
	v_mfma_f32_32x32x16_bf16 v[150:165], v[202:205], v[250:253], v[150:165]
	s_mov_b32 m0, s51
	v_lshl_add_u64 v[64:65], v[64:65], 0, s[44:45]
	global_load_lds_dwordx4 v[64:65], off
	global_load_lds_dwordx4 v[64:65], off offset:1024
	v_mfma_f32_32x32x16_bf16 v[166:181], v[202:205], v[74:77], v[166:181]
	ds_read_b128 v[202:205], v115 offset:32768
	s_mov_b32 m0, s54
	v_lshl_add_u64 v[66:67], v[66:67], 0, s[44:45]
	global_load_lds_dwordx4 v[66:67], off
	global_load_lds_dwordx4 v[66:67], off offset:1024
	v_mfma_f32_32x32x16_bf16 v[16:31], v[206:209], v[214:217], v[16:31]
	ds_read_b128 v[214:217], v119 offset:40960
	s_mov_b32 m0, s57
	v_lshl_add_u64 v[148:149], v[66:67], 0, s[72:73]
	global_load_lds_dwordx4 v[148:149], off
	global_load_lds_dwordx4 v[148:149], off offset:1024
	v_mfma_f32_32x32x16_bf16 v[0:15], v[206:209], v[244:247], v[0:15]
	ds_read_b128 v[244:247], v119 offset:43008
	v_mfma_f32_32x32x16_bf16 v[184:199], v[206:209], v[250:253], v[184:199]
	ds_read_b128 v[250:253], v122 offset:57344
	v_mfma_f32_32x32x16_bf16 v[226:241], v[206:209], v[74:77], v[226:241]
	ds_read_b128 v[206:209], v115 offset:34816
	ds_read_b128 v[74:77], v122 offset:59392
	s_waitcnt lgkmcnt(6)
	v_mfma_f32_32x32x16_bf16 v[48:63], v[110:113], v[132:135], v[48:63]
	v_mfma_f32_32x32x16_bf16 v[32:47], v[110:113], v[136:139], v[32:47]
	v_mfma_f32_32x32x16_bf16 v[150:165], v[110:113], v[140:143], v[150:165]
	v_mfma_f32_32x32x16_bf16 v[166:181], v[110:113], v[144:147], v[166:181]
	v_mfma_f32_32x32x16_bf16 v[16:31], v[128:131], v[132:135], v[16:31]
	v_mfma_f32_32x32x16_bf16 v[0:15], v[128:131], v[136:139], v[0:15]
	v_mfma_f32_32x32x16_bf16 v[184:199], v[128:131], v[140:143], v[184:199]
	v_mfma_f32_32x32x16_bf16 v[226:241], v[128:131], v[144:147], v[226:241]
	s_waitcnt vmcnt(6)
	s_waitcnt lgkmcnt(0)
	s_barrier
	ds_read_b128 v[110:113], v109
	ds_read_b128 v[132:135], v114 offset:8192
	v_mfma_f32_32x32x16_bf16 v[48:63], v[202:205], v[214:217], v[48:63]
	ds_read_b128 v[136:139], v114 offset:10240
	ds_read_b128 v[140:143], v114 offset:49152
	v_mfma_f32_32x32x16_bf16 v[32:47], v[202:205], v[244:247], v[32:47]
	ds_read_b128 v[144:147], v114 offset:51200
	ds_read_b128 v[128:131], v109 offset:2048
	v_mfma_f32_32x32x16_bf16 v[150:165], v[202:205], v[250:253], v[150:165]
	s_mov_b32 m0, s52
	v_lshl_add_u64 v[64:65], v[64:65], 0, s[44:45]
	global_load_lds_dwordx4 v[64:65], off
	global_load_lds_dwordx4 v[64:65], off offset:1024
	v_mfma_f32_32x32x16_bf16 v[166:181], v[202:205], v[74:77], v[166:181]
	ds_read_b128 v[202:205], v115
	s_mov_b32 m0, s55
	v_lshl_add_u64 v[66:67], v[66:67], 0, s[44:45]
	global_load_lds_dwordx4 v[66:67], off
	global_load_lds_dwordx4 v[66:67], off offset:1024
	v_mfma_f32_32x32x16_bf16 v[16:31], v[206:209], v[214:217], v[16:31]
	ds_read_b128 v[214:217], v119 offset:8192
	s_mov_b32 m0, s58
	v_lshl_add_u64 v[148:149], v[66:67], 0, s[72:73]
	global_load_lds_dwordx4 v[148:149], off
	global_load_lds_dwordx4 v[148:149], off offset:1024
	v_mfma_f32_32x32x16_bf16 v[0:15], v[206:209], v[244:247], v[0:15]
	ds_read_b128 v[244:247], v119 offset:10240
	v_mfma_f32_32x32x16_bf16 v[184:199], v[206:209], v[250:253], v[184:199]
	ds_read_b128 v[250:253], v119 offset:49152
	v_mfma_f32_32x32x16_bf16 v[226:241], v[206:209], v[74:77], v[226:241]
	ds_read_b128 v[206:209], v115 offset:2048
	ds_read_b128 v[74:77], v119 offset:51200
	s_waitcnt lgkmcnt(6)
	v_mfma_f32_32x32x16_bf16 v[48:63], v[110:113], v[132:135], v[48:63]
	v_mfma_f32_32x32x16_bf16 v[32:47], v[110:113], v[136:139], v[32:47]
	v_mfma_f32_32x32x16_bf16 v[150:165], v[110:113], v[140:143], v[150:165]
	v_mfma_f32_32x32x16_bf16 v[166:181], v[110:113], v[144:147], v[166:181]
	v_mfma_f32_32x32x16_bf16 v[16:31], v[128:131], v[132:135], v[16:31]
	v_mfma_f32_32x32x16_bf16 v[0:15], v[128:131], v[136:139], v[0:15]
	v_mfma_f32_32x32x16_bf16 v[184:199], v[128:131], v[140:143], v[184:199]
	v_mfma_f32_32x32x16_bf16 v[226:241], v[128:131], v[144:147], v[226:241]
	s_waitcnt vmcnt(6)
	s_waitcnt lgkmcnt(0)
	s_barrier
	ds_read_b128 v[110:113], v109 offset:16384
	ds_read_b128 v[132:135], v114 offset:24576
	v_mfma_f32_32x32x16_bf16 v[48:63], v[202:205], v[214:217], v[48:63]
	ds_read_b128 v[136:139], v114 offset:26624
	ds_read_b128 v[140:143], v121 offset:40960
	v_mfma_f32_32x32x16_bf16 v[32:47], v[202:205], v[244:247], v[32:47]
	ds_read_b128 v[144:147], v121 offset:43008
	ds_read_b128 v[128:131], v109 offset:18432
	v_mfma_f32_32x32x16_bf16 v[150:165], v[202:205], v[250:253], v[150:165]
	s_mov_b32 m0, s50
	v_lshl_add_u64 v[64:65], v[64:65], 0, s[44:45]
	global_load_lds_dwordx4 v[64:65], off
	global_load_lds_dwordx4 v[64:65], off offset:1024
	v_mfma_f32_32x32x16_bf16 v[166:181], v[202:205], v[74:77], v[166:181]
	ds_read_b128 v[202:205], v115 offset:16384
	s_mov_b32 m0, s53
	v_lshl_add_u64 v[66:67], v[66:67], 0, s[44:45]
	global_load_lds_dwordx4 v[66:67], off
	global_load_lds_dwordx4 v[66:67], off offset:1024
	v_mfma_f32_32x32x16_bf16 v[16:31], v[206:209], v[214:217], v[16:31]
	ds_read_b128 v[214:217], v119 offset:24576
	s_mov_b32 m0, s56
	v_lshl_add_u64 v[148:149], v[66:67], 0, s[72:73]
	global_load_lds_dwordx4 v[148:149], off
	global_load_lds_dwordx4 v[148:149], off offset:1024
	v_mfma_f32_32x32x16_bf16 v[0:15], v[206:209], v[244:247], v[0:15]
	ds_read_b128 v[244:247], v119 offset:26624
	v_mfma_f32_32x32x16_bf16 v[184:199], v[206:209], v[250:253], v[184:199]
	ds_read_b128 v[250:253], v122 offset:40960
	v_mfma_f32_32x32x16_bf16 v[226:241], v[206:209], v[74:77], v[226:241]
	ds_read_b128 v[206:209], v115 offset:18432
	ds_read_b128 v[74:77], v122 offset:43008
	s_waitcnt lgkmcnt(6)
	v_mfma_f32_32x32x16_bf16 v[48:63], v[110:113], v[132:135], v[48:63]
	v_mfma_f32_32x32x16_bf16 v[32:47], v[110:113], v[136:139], v[32:47]
	v_mfma_f32_32x32x16_bf16 v[150:165], v[110:113], v[140:143], v[150:165]
	v_mfma_f32_32x32x16_bf16 v[166:181], v[110:113], v[144:147], v[166:181]
	v_mfma_f32_32x32x16_bf16 v[16:31], v[128:131], v[132:135], v[16:31]
	v_mfma_f32_32x32x16_bf16 v[0:15], v[128:131], v[136:139], v[0:15]
	v_mfma_f32_32x32x16_bf16 v[184:199], v[128:131], v[140:143], v[184:199]
	v_mfma_f32_32x32x16_bf16 v[226:241], v[128:131], v[144:147], v[226:241]
	s_waitcnt vmcnt(6)
	s_waitcnt lgkmcnt(0)
	s_barrier
	ds_read_b128 v[110:113], v109 offset:32768
	ds_read_b128 v[132:135], v114 offset:40960
	v_mfma_f32_32x32x16_bf16 v[48:63], v[202:205], v[214:217], v[48:63]
	ds_read_b128 v[136:139], v114 offset:43008
	ds_read_b128 v[140:143], v121 offset:57344
	v_mfma_f32_32x32x16_bf16 v[32:47], v[202:205], v[244:247], v[32:47]
	ds_read_b128 v[144:147], v121 offset:59392
	ds_read_b128 v[128:131], v109 offset:34816
	v_mfma_f32_32x32x16_bf16 v[150:165], v[202:205], v[250:253], v[150:165]
	s_mov_b32 m0, s51
	v_lshl_add_u64 v[64:65], v[64:65], 0, s[44:45]
	global_load_lds_dwordx4 v[64:65], off
	global_load_lds_dwordx4 v[64:65], off offset:1024
	v_mfma_f32_32x32x16_bf16 v[166:181], v[202:205], v[74:77], v[166:181]
	ds_read_b128 v[202:205], v115 offset:32768
	s_mov_b32 m0, s54
	v_lshl_add_u64 v[66:67], v[66:67], 0, s[44:45]
	global_load_lds_dwordx4 v[66:67], off
	global_load_lds_dwordx4 v[66:67], off offset:1024
	v_mfma_f32_32x32x16_bf16 v[16:31], v[206:209], v[214:217], v[16:31]
	ds_read_b128 v[214:217], v119 offset:40960
	s_mov_b32 m0, s57
	v_lshl_add_u64 v[148:149], v[66:67], 0, s[72:73]
	global_load_lds_dwordx4 v[148:149], off
	global_load_lds_dwordx4 v[148:149], off offset:1024
	v_mfma_f32_32x32x16_bf16 v[0:15], v[206:209], v[244:247], v[0:15]
	ds_read_b128 v[244:247], v119 offset:43008
	v_mfma_f32_32x32x16_bf16 v[184:199], v[206:209], v[250:253], v[184:199]
	ds_read_b128 v[250:253], v122 offset:57344
	v_mfma_f32_32x32x16_bf16 v[226:241], v[206:209], v[74:77], v[226:241]
	ds_read_b128 v[206:209], v115 offset:34816
	ds_read_b128 v[74:77], v122 offset:59392
	s_waitcnt lgkmcnt(6)
	v_mfma_f32_32x32x16_bf16 v[48:63], v[110:113], v[132:135], v[48:63]
	v_mfma_f32_32x32x16_bf16 v[32:47], v[110:113], v[136:139], v[32:47]
	v_mfma_f32_32x32x16_bf16 v[150:165], v[110:113], v[140:143], v[150:165]
	v_mfma_f32_32x32x16_bf16 v[166:181], v[110:113], v[144:147], v[166:181]
	v_mfma_f32_32x32x16_bf16 v[16:31], v[128:131], v[132:135], v[16:31]
	v_mfma_f32_32x32x16_bf16 v[0:15], v[128:131], v[136:139], v[0:15]
	v_mfma_f32_32x32x16_bf16 v[184:199], v[128:131], v[140:143], v[184:199]
	v_mfma_f32_32x32x16_bf16 v[226:241], v[128:131], v[144:147], v[226:241]
	s_waitcnt vmcnt(6)
	s_waitcnt lgkmcnt(0)
	s_barrier
	ds_read_b128 v[110:113], v109
	ds_read_b128 v[132:135], v114 offset:8192
	v_mfma_f32_32x32x16_bf16 v[48:63], v[202:205], v[214:217], v[48:63]
	ds_read_b128 v[136:139], v114 offset:10240
	ds_read_b128 v[140:143], v114 offset:49152
	v_mfma_f32_32x32x16_bf16 v[32:47], v[202:205], v[244:247], v[32:47]
	ds_read_b128 v[144:147], v114 offset:51200
	ds_read_b128 v[128:131], v109 offset:2048
	v_mfma_f32_32x32x16_bf16 v[150:165], v[202:205], v[250:253], v[150:165]
	s_mov_b32 m0, s52
	v_lshl_add_u64 v[64:65], v[64:65], 0, s[44:45]
	global_load_lds_dwordx4 v[64:65], off
	global_load_lds_dwordx4 v[64:65], off offset:1024
	v_mfma_f32_32x32x16_bf16 v[166:181], v[202:205], v[74:77], v[166:181]
	ds_read_b128 v[202:205], v115
	s_mov_b32 m0, s55
	v_lshl_add_u64 v[66:67], v[66:67], 0, s[44:45]
	global_load_lds_dwordx4 v[66:67], off
	global_load_lds_dwordx4 v[66:67], off offset:1024
	v_mfma_f32_32x32x16_bf16 v[16:31], v[206:209], v[214:217], v[16:31]
	ds_read_b128 v[214:217], v119 offset:8192
	s_mov_b32 m0, s58
	v_lshl_add_u64 v[148:149], v[66:67], 0, s[72:73]
	global_load_lds_dwordx4 v[148:149], off
	global_load_lds_dwordx4 v[148:149], off offset:1024
	v_mfma_f32_32x32x16_bf16 v[0:15], v[206:209], v[244:247], v[0:15]
	ds_read_b128 v[244:247], v119 offset:10240
	v_mfma_f32_32x32x16_bf16 v[184:199], v[206:209], v[250:253], v[184:199]
	ds_read_b128 v[250:253], v119 offset:49152
	v_mfma_f32_32x32x16_bf16 v[226:241], v[206:209], v[74:77], v[226:241]
	ds_read_b128 v[206:209], v115 offset:2048
	ds_read_b128 v[74:77], v119 offset:51200
	s_waitcnt lgkmcnt(6)
	v_mfma_f32_32x32x16_bf16 v[48:63], v[110:113], v[132:135], v[48:63]
	v_mfma_f32_32x32x16_bf16 v[32:47], v[110:113], v[136:139], v[32:47]
	v_mfma_f32_32x32x16_bf16 v[150:165], v[110:113], v[140:143], v[150:165]
	v_mfma_f32_32x32x16_bf16 v[166:181], v[110:113], v[144:147], v[166:181]
	v_mfma_f32_32x32x16_bf16 v[16:31], v[128:131], v[132:135], v[16:31]
	v_mfma_f32_32x32x16_bf16 v[0:15], v[128:131], v[136:139], v[0:15]
	v_mfma_f32_32x32x16_bf16 v[184:199], v[128:131], v[140:143], v[184:199]
	v_mfma_f32_32x32x16_bf16 v[226:241], v[128:131], v[144:147], v[226:241]
	s_waitcnt vmcnt(6)
	s_waitcnt lgkmcnt(0)
	s_barrier
	ds_read_b128 v[110:113], v109 offset:16384
	ds_read_b128 v[132:135], v114 offset:24576
	v_mfma_f32_32x32x16_bf16 v[48:63], v[202:205], v[214:217], v[48:63]
	ds_read_b128 v[136:139], v114 offset:26624
	ds_read_b128 v[140:143], v121 offset:40960
	v_mfma_f32_32x32x16_bf16 v[32:47], v[202:205], v[244:247], v[32:47]
	ds_read_b128 v[144:147], v121 offset:43008
	ds_read_b128 v[128:131], v109 offset:18432
	v_mfma_f32_32x32x16_bf16 v[150:165], v[202:205], v[250:253], v[150:165]
	s_mov_b32 m0, s50
	v_lshl_add_u64 v[64:65], v[64:65], 0, s[44:45]
	global_load_lds_dwordx4 v[64:65], off
	global_load_lds_dwordx4 v[64:65], off offset:1024
	v_mfma_f32_32x32x16_bf16 v[166:181], v[202:205], v[74:77], v[166:181]
	ds_read_b128 v[202:205], v115 offset:16384
	s_mov_b32 m0, s53
	v_lshl_add_u64 v[66:67], v[66:67], 0, s[44:45]
	global_load_lds_dwordx4 v[66:67], off
	global_load_lds_dwordx4 v[66:67], off offset:1024
	v_mfma_f32_32x32x16_bf16 v[16:31], v[206:209], v[214:217], v[16:31]
	ds_read_b128 v[214:217], v119 offset:24576
	s_mov_b32 m0, s56
	v_lshl_add_u64 v[148:149], v[66:67], 0, s[72:73]
	global_load_lds_dwordx4 v[148:149], off
	global_load_lds_dwordx4 v[148:149], off offset:1024
	v_mfma_f32_32x32x16_bf16 v[0:15], v[206:209], v[244:247], v[0:15]
	ds_read_b128 v[244:247], v119 offset:26624
	v_mfma_f32_32x32x16_bf16 v[184:199], v[206:209], v[250:253], v[184:199]
	ds_read_b128 v[250:253], v122 offset:40960
	v_mfma_f32_32x32x16_bf16 v[226:241], v[206:209], v[74:77], v[226:241]
	ds_read_b128 v[206:209], v115 offset:18432
	ds_read_b128 v[74:77], v122 offset:43008
	s_waitcnt lgkmcnt(6)
	v_mfma_f32_32x32x16_bf16 v[48:63], v[110:113], v[132:135], v[48:63]
	v_mfma_f32_32x32x16_bf16 v[32:47], v[110:113], v[136:139], v[32:47]
	v_mfma_f32_32x32x16_bf16 v[150:165], v[110:113], v[140:143], v[150:165]
	v_mfma_f32_32x32x16_bf16 v[166:181], v[110:113], v[144:147], v[166:181]
	v_mfma_f32_32x32x16_bf16 v[16:31], v[128:131], v[132:135], v[16:31]
	v_mfma_f32_32x32x16_bf16 v[0:15], v[128:131], v[136:139], v[0:15]
	v_mfma_f32_32x32x16_bf16 v[184:199], v[128:131], v[140:143], v[184:199]
	v_mfma_f32_32x32x16_bf16 v[226:241], v[128:131], v[144:147], v[226:241]
	s_waitcnt vmcnt(6)
	s_waitcnt lgkmcnt(0)
	s_barrier
	ds_read_b128 v[110:113], v109 offset:32768
	ds_read_b128 v[132:135], v114 offset:40960
	v_mfma_f32_32x32x16_bf16 v[48:63], v[202:205], v[214:217], v[48:63]
	ds_read_b128 v[136:139], v114 offset:43008
	ds_read_b128 v[140:143], v121 offset:57344
	v_mfma_f32_32x32x16_bf16 v[32:47], v[202:205], v[244:247], v[32:47]
	ds_read_b128 v[144:147], v121 offset:59392
	ds_read_b128 v[128:131], v109 offset:34816
	v_mfma_f32_32x32x16_bf16 v[150:165], v[202:205], v[250:253], v[150:165]
	s_mov_b32 m0, s51
	v_lshl_add_u64 v[64:65], v[64:65], 0, s[44:45]
	global_load_lds_dwordx4 v[64:65], off
	global_load_lds_dwordx4 v[64:65], off offset:1024
	v_mfma_f32_32x32x16_bf16 v[166:181], v[202:205], v[74:77], v[166:181]
	ds_read_b128 v[202:205], v115 offset:32768
	s_mov_b32 m0, s54
	v_lshl_add_u64 v[66:67], v[66:67], 0, s[44:45]
	global_load_lds_dwordx4 v[66:67], off
	global_load_lds_dwordx4 v[66:67], off offset:1024
	v_mfma_f32_32x32x16_bf16 v[16:31], v[206:209], v[214:217], v[16:31]
	ds_read_b128 v[214:217], v119 offset:40960
	s_mov_b32 m0, s57
	v_lshl_add_u64 v[148:149], v[66:67], 0, s[72:73]
	global_load_lds_dwordx4 v[148:149], off
	global_load_lds_dwordx4 v[148:149], off offset:1024
	v_mfma_f32_32x32x16_bf16 v[0:15], v[206:209], v[244:247], v[0:15]
	ds_read_b128 v[244:247], v119 offset:43008
	v_mfma_f32_32x32x16_bf16 v[184:199], v[206:209], v[250:253], v[184:199]
	ds_read_b128 v[250:253], v122 offset:57344
	v_mfma_f32_32x32x16_bf16 v[226:241], v[206:209], v[74:77], v[226:241]
	ds_read_b128 v[206:209], v115 offset:34816
	ds_read_b128 v[74:77], v122 offset:59392
	s_waitcnt lgkmcnt(6)
	v_mfma_f32_32x32x16_bf16 v[48:63], v[110:113], v[132:135], v[48:63]
	v_mfma_f32_32x32x16_bf16 v[32:47], v[110:113], v[136:139], v[32:47]
	v_mfma_f32_32x32x16_bf16 v[150:165], v[110:113], v[140:143], v[150:165]
	v_mfma_f32_32x32x16_bf16 v[166:181], v[110:113], v[144:147], v[166:181]
	v_mfma_f32_32x32x16_bf16 v[16:31], v[128:131], v[132:135], v[16:31]
	v_mfma_f32_32x32x16_bf16 v[0:15], v[128:131], v[136:139], v[0:15]
	v_mfma_f32_32x32x16_bf16 v[184:199], v[128:131], v[140:143], v[184:199]
	v_mfma_f32_32x32x16_bf16 v[226:241], v[128:131], v[144:147], v[226:241]
	s_waitcnt vmcnt(6)
	s_waitcnt lgkmcnt(0)
	s_barrier
	ds_read_b128 v[110:113], v109
	ds_read_b128 v[132:135], v114 offset:8192
	v_mfma_f32_32x32x16_bf16 v[48:63], v[202:205], v[214:217], v[48:63]
	ds_read_b128 v[136:139], v114 offset:10240
	ds_read_b128 v[140:143], v114 offset:49152
	v_mfma_f32_32x32x16_bf16 v[32:47], v[202:205], v[244:247], v[32:47]
	ds_read_b128 v[144:147], v114 offset:51200
	ds_read_b128 v[128:131], v109 offset:2048
	v_mfma_f32_32x32x16_bf16 v[150:165], v[202:205], v[250:253], v[150:165]
	s_mov_b32 m0, s52
	v_lshl_add_u64 v[64:65], v[64:65], 0, s[44:45]
	global_load_lds_dwordx4 v[64:65], off
	global_load_lds_dwordx4 v[64:65], off offset:1024
	v_mfma_f32_32x32x16_bf16 v[166:181], v[202:205], v[74:77], v[166:181]
	ds_read_b128 v[202:205], v115
	s_mov_b32 m0, s55
	v_lshl_add_u64 v[66:67], v[66:67], 0, s[44:45]
	global_load_lds_dwordx4 v[66:67], off
	global_load_lds_dwordx4 v[66:67], off offset:1024
	v_mfma_f32_32x32x16_bf16 v[16:31], v[206:209], v[214:217], v[16:31]
	ds_read_b128 v[214:217], v119 offset:8192
	s_mov_b32 m0, s58
	v_lshl_add_u64 v[148:149], v[66:67], 0, s[72:73]
	global_load_lds_dwordx4 v[148:149], off
	global_load_lds_dwordx4 v[148:149], off offset:1024
	v_mfma_f32_32x32x16_bf16 v[0:15], v[206:209], v[244:247], v[0:15]
	ds_read_b128 v[244:247], v119 offset:10240
	v_mfma_f32_32x32x16_bf16 v[184:199], v[206:209], v[250:253], v[184:199]
	ds_read_b128 v[250:253], v119 offset:49152
	v_mfma_f32_32x32x16_bf16 v[226:241], v[206:209], v[74:77], v[226:241]
	ds_read_b128 v[206:209], v115 offset:2048
	ds_read_b128 v[74:77], v119 offset:51200
	s_waitcnt lgkmcnt(6)
	v_mfma_f32_32x32x16_bf16 v[48:63], v[110:113], v[132:135], v[48:63]
	v_mfma_f32_32x32x16_bf16 v[32:47], v[110:113], v[136:139], v[32:47]
	v_mfma_f32_32x32x16_bf16 v[150:165], v[110:113], v[140:143], v[150:165]
	v_mfma_f32_32x32x16_bf16 v[166:181], v[110:113], v[144:147], v[166:181]
	v_mfma_f32_32x32x16_bf16 v[16:31], v[128:131], v[132:135], v[16:31]
	v_mfma_f32_32x32x16_bf16 v[0:15], v[128:131], v[136:139], v[0:15]
	v_mfma_f32_32x32x16_bf16 v[184:199], v[128:131], v[140:143], v[184:199]
	v_mfma_f32_32x32x16_bf16 v[226:241], v[128:131], v[144:147], v[226:241]
	s_waitcnt vmcnt(6)
	s_waitcnt lgkmcnt(0)
	s_barrier
	ds_read_b128 v[110:113], v109 offset:16384
	ds_read_b128 v[132:135], v114 offset:24576
	v_mfma_f32_32x32x16_bf16 v[48:63], v[202:205], v[214:217], v[48:63]
	ds_read_b128 v[136:139], v114 offset:26624
	ds_read_b128 v[140:143], v121 offset:40960
	v_mfma_f32_32x32x16_bf16 v[32:47], v[202:205], v[244:247], v[32:47]
	ds_read_b128 v[144:147], v121 offset:43008
	ds_read_b128 v[128:131], v109 offset:18432
	v_mfma_f32_32x32x16_bf16 v[150:165], v[202:205], v[250:253], v[150:165]
	s_mov_b32 m0, s50
	v_lshl_add_u64 v[64:65], v[64:65], 0, s[44:45]
	global_load_lds_dwordx4 v[64:65], off
	global_load_lds_dwordx4 v[64:65], off offset:1024
	v_mfma_f32_32x32x16_bf16 v[166:181], v[202:205], v[74:77], v[166:181]
	ds_read_b128 v[202:205], v115 offset:16384
	s_mov_b32 m0, s53
	v_lshl_add_u64 v[66:67], v[66:67], 0, s[44:45]
	global_load_lds_dwordx4 v[66:67], off
	global_load_lds_dwordx4 v[66:67], off offset:1024
	v_mfma_f32_32x32x16_bf16 v[16:31], v[206:209], v[214:217], v[16:31]
	ds_read_b128 v[214:217], v119 offset:24576
	s_mov_b32 m0, s56
	v_lshl_add_u64 v[148:149], v[66:67], 0, s[72:73]
	global_load_lds_dwordx4 v[148:149], off
	global_load_lds_dwordx4 v[148:149], off offset:1024
	v_mfma_f32_32x32x16_bf16 v[0:15], v[206:209], v[244:247], v[0:15]
	ds_read_b128 v[244:247], v119 offset:26624
	v_mfma_f32_32x32x16_bf16 v[184:199], v[206:209], v[250:253], v[184:199]
	ds_read_b128 v[250:253], v122 offset:40960
	v_mfma_f32_32x32x16_bf16 v[226:241], v[206:209], v[74:77], v[226:241]
	ds_read_b128 v[206:209], v115 offset:18432
	ds_read_b128 v[74:77], v122 offset:43008
	s_waitcnt lgkmcnt(6)
	v_mfma_f32_32x32x16_bf16 v[48:63], v[110:113], v[132:135], v[48:63]
	v_mfma_f32_32x32x16_bf16 v[32:47], v[110:113], v[136:139], v[32:47]
	v_mfma_f32_32x32x16_bf16 v[150:165], v[110:113], v[140:143], v[150:165]
	v_mfma_f32_32x32x16_bf16 v[166:181], v[110:113], v[144:147], v[166:181]
	v_mfma_f32_32x32x16_bf16 v[16:31], v[128:131], v[132:135], v[16:31]
	v_mfma_f32_32x32x16_bf16 v[0:15], v[128:131], v[136:139], v[0:15]
	v_mfma_f32_32x32x16_bf16 v[184:199], v[128:131], v[140:143], v[184:199]
	v_mfma_f32_32x32x16_bf16 v[226:241], v[128:131], v[144:147], v[226:241]
	s_waitcnt vmcnt(6)
	s_waitcnt lgkmcnt(0)
	s_barrier
	ds_read_b128 v[110:113], v109 offset:32768
	ds_read_b128 v[132:135], v114 offset:40960
	v_mfma_f32_32x32x16_bf16 v[48:63], v[202:205], v[214:217], v[48:63]
	ds_read_b128 v[136:139], v114 offset:43008
	ds_read_b128 v[140:143], v121 offset:57344
	v_mfma_f32_32x32x16_bf16 v[32:47], v[202:205], v[244:247], v[32:47]
	ds_read_b128 v[144:147], v121 offset:59392
	ds_read_b128 v[128:131], v109 offset:34816
	v_mfma_f32_32x32x16_bf16 v[150:165], v[202:205], v[250:253], v[150:165]
	s_mov_b32 m0, s51
	v_lshl_add_u64 v[64:65], v[64:65], 0, s[44:45]
	global_load_lds_dwordx4 v[64:65], off
	global_load_lds_dwordx4 v[64:65], off offset:1024
	v_mfma_f32_32x32x16_bf16 v[166:181], v[202:205], v[74:77], v[166:181]
	ds_read_b128 v[202:205], v115 offset:32768
	s_mov_b32 m0, s54
	v_lshl_add_u64 v[66:67], v[66:67], 0, s[44:45]
	global_load_lds_dwordx4 v[66:67], off
	global_load_lds_dwordx4 v[66:67], off offset:1024
	v_mfma_f32_32x32x16_bf16 v[16:31], v[206:209], v[214:217], v[16:31]
	ds_read_b128 v[214:217], v119 offset:40960
	s_mov_b32 m0, s57
	v_lshl_add_u64 v[148:149], v[66:67], 0, s[72:73]
	global_load_lds_dwordx4 v[148:149], off
	global_load_lds_dwordx4 v[148:149], off offset:1024
	v_mfma_f32_32x32x16_bf16 v[0:15], v[206:209], v[244:247], v[0:15]
	ds_read_b128 v[244:247], v119 offset:43008
	v_mfma_f32_32x32x16_bf16 v[184:199], v[206:209], v[250:253], v[184:199]
	ds_read_b128 v[250:253], v122 offset:57344
	v_mfma_f32_32x32x16_bf16 v[226:241], v[206:209], v[74:77], v[226:241]
	ds_read_b128 v[206:209], v115 offset:34816
	ds_read_b128 v[74:77], v122 offset:59392
	s_waitcnt lgkmcnt(6)
	v_mfma_f32_32x32x16_bf16 v[48:63], v[110:113], v[132:135], v[48:63]
	v_mfma_f32_32x32x16_bf16 v[32:47], v[110:113], v[136:139], v[32:47]
	v_mfma_f32_32x32x16_bf16 v[150:165], v[110:113], v[140:143], v[150:165]
	v_mfma_f32_32x32x16_bf16 v[166:181], v[110:113], v[144:147], v[166:181]
	v_mfma_f32_32x32x16_bf16 v[16:31], v[128:131], v[132:135], v[16:31]
	v_mfma_f32_32x32x16_bf16 v[0:15], v[128:131], v[136:139], v[0:15]
	v_mfma_f32_32x32x16_bf16 v[184:199], v[128:131], v[140:143], v[184:199]
	v_mfma_f32_32x32x16_bf16 v[226:241], v[128:131], v[144:147], v[226:241]
	s_waitcnt vmcnt(6)
	s_waitcnt lgkmcnt(0)
	s_barrier
	ds_read_b128 v[110:113], v109
	ds_read_b128 v[132:135], v114 offset:8192
	v_mfma_f32_32x32x16_bf16 v[48:63], v[202:205], v[214:217], v[48:63]
	ds_read_b128 v[136:139], v114 offset:10240
	ds_read_b128 v[140:143], v114 offset:49152
	v_mfma_f32_32x32x16_bf16 v[32:47], v[202:205], v[244:247], v[32:47]
	ds_read_b128 v[144:147], v114 offset:51200
	ds_read_b128 v[128:131], v109 offset:2048
	v_mfma_f32_32x32x16_bf16 v[150:165], v[202:205], v[250:253], v[150:165]
	s_mov_b32 m0, s52
	v_lshl_add_u64 v[64:65], v[64:65], 0, s[44:45]
	global_load_lds_dwordx4 v[64:65], off
	global_load_lds_dwordx4 v[64:65], off offset:1024
	v_mfma_f32_32x32x16_bf16 v[166:181], v[202:205], v[74:77], v[166:181]
	ds_read_b128 v[202:205], v115
	s_mov_b32 m0, s55
	v_lshl_add_u64 v[66:67], v[66:67], 0, s[44:45]
	global_load_lds_dwordx4 v[66:67], off
	global_load_lds_dwordx4 v[66:67], off offset:1024
	v_mfma_f32_32x32x16_bf16 v[16:31], v[206:209], v[214:217], v[16:31]
	ds_read_b128 v[214:217], v119 offset:8192
	s_mov_b32 m0, s58
	v_lshl_add_u64 v[148:149], v[66:67], 0, s[72:73]
	global_load_lds_dwordx4 v[148:149], off
	global_load_lds_dwordx4 v[148:149], off offset:1024
	v_mfma_f32_32x32x16_bf16 v[0:15], v[206:209], v[244:247], v[0:15]
	ds_read_b128 v[244:247], v119 offset:10240
	v_mfma_f32_32x32x16_bf16 v[184:199], v[206:209], v[250:253], v[184:199]
	ds_read_b128 v[250:253], v119 offset:49152
	v_mfma_f32_32x32x16_bf16 v[226:241], v[206:209], v[74:77], v[226:241]
	ds_read_b128 v[206:209], v115 offset:2048
	ds_read_b128 v[74:77], v119 offset:51200
	s_waitcnt lgkmcnt(6)
	v_mfma_f32_32x32x16_bf16 v[48:63], v[110:113], v[132:135], v[48:63]
	v_mfma_f32_32x32x16_bf16 v[32:47], v[110:113], v[136:139], v[32:47]
	v_mfma_f32_32x32x16_bf16 v[150:165], v[110:113], v[140:143], v[150:165]
	v_mfma_f32_32x32x16_bf16 v[166:181], v[110:113], v[144:147], v[166:181]
	v_mfma_f32_32x32x16_bf16 v[16:31], v[128:131], v[132:135], v[16:31]
	v_mfma_f32_32x32x16_bf16 v[0:15], v[128:131], v[136:139], v[0:15]
	v_mfma_f32_32x32x16_bf16 v[184:199], v[128:131], v[140:143], v[184:199]
	v_mfma_f32_32x32x16_bf16 v[226:241], v[128:131], v[144:147], v[226:241]
	s_waitcnt vmcnt(6)
	s_waitcnt lgkmcnt(0)
	s_barrier
	ds_read_b128 v[110:113], v109 offset:16384
	ds_read_b128 v[132:135], v114 offset:24576
	v_mfma_f32_32x32x16_bf16 v[48:63], v[202:205], v[214:217], v[48:63]
	ds_read_b128 v[136:139], v114 offset:26624
	ds_read_b128 v[140:143], v121 offset:40960
	v_mfma_f32_32x32x16_bf16 v[32:47], v[202:205], v[244:247], v[32:47]
	ds_read_b128 v[144:147], v121 offset:43008
	ds_read_b128 v[128:131], v109 offset:18432
	v_mfma_f32_32x32x16_bf16 v[150:165], v[202:205], v[250:253], v[150:165]
	s_mov_b32 m0, s50
	v_lshl_add_u64 v[64:65], v[64:65], 0, s[44:45]
	global_load_lds_dwordx4 v[64:65], off
	global_load_lds_dwordx4 v[64:65], off offset:1024
	v_mfma_f32_32x32x16_bf16 v[166:181], v[202:205], v[74:77], v[166:181]
	ds_read_b128 v[202:205], v115 offset:16384
	s_mov_b32 m0, s53
	v_lshl_add_u64 v[66:67], v[66:67], 0, s[44:45]
	global_load_lds_dwordx4 v[66:67], off
	global_load_lds_dwordx4 v[66:67], off offset:1024
	v_mfma_f32_32x32x16_bf16 v[16:31], v[206:209], v[214:217], v[16:31]
	ds_read_b128 v[214:217], v119 offset:24576
	s_mov_b32 m0, s56
	v_lshl_add_u64 v[148:149], v[66:67], 0, s[72:73]
	global_load_lds_dwordx4 v[148:149], off
	global_load_lds_dwordx4 v[148:149], off offset:1024
	v_mfma_f32_32x32x16_bf16 v[0:15], v[206:209], v[244:247], v[0:15]
	ds_read_b128 v[244:247], v119 offset:26624
	v_mfma_f32_32x32x16_bf16 v[184:199], v[206:209], v[250:253], v[184:199]
	ds_read_b128 v[250:253], v122 offset:40960
	v_mfma_f32_32x32x16_bf16 v[226:241], v[206:209], v[74:77], v[226:241]
	ds_read_b128 v[206:209], v115 offset:18432
	ds_read_b128 v[74:77], v122 offset:43008
	s_waitcnt lgkmcnt(6)
	v_mfma_f32_32x32x16_bf16 v[48:63], v[110:113], v[132:135], v[48:63]
	v_mfma_f32_32x32x16_bf16 v[32:47], v[110:113], v[136:139], v[32:47]
	v_mfma_f32_32x32x16_bf16 v[150:165], v[110:113], v[140:143], v[150:165]
	v_mfma_f32_32x32x16_bf16 v[166:181], v[110:113], v[144:147], v[166:181]
	v_mfma_f32_32x32x16_bf16 v[16:31], v[128:131], v[132:135], v[16:31]
	v_mfma_f32_32x32x16_bf16 v[0:15], v[128:131], v[136:139], v[0:15]
	v_mfma_f32_32x32x16_bf16 v[184:199], v[128:131], v[140:143], v[184:199]
	v_mfma_f32_32x32x16_bf16 v[226:241], v[128:131], v[144:147], v[226:241]
	s_waitcnt vmcnt(6)
	s_waitcnt lgkmcnt(0)
	s_barrier
	ds_read_b128 v[110:113], v109 offset:32768
	ds_read_b128 v[132:135], v114 offset:40960
	v_mfma_f32_32x32x16_bf16 v[48:63], v[202:205], v[214:217], v[48:63]
	ds_read_b128 v[136:139], v114 offset:43008
	ds_read_b128 v[140:143], v121 offset:57344
	v_mfma_f32_32x32x16_bf16 v[32:47], v[202:205], v[244:247], v[32:47]
	ds_read_b128 v[144:147], v121 offset:59392
	ds_read_b128 v[128:131], v109 offset:34816
	v_mfma_f32_32x32x16_bf16 v[150:165], v[202:205], v[250:253], v[150:165]
	s_mov_b32 m0, s51
	v_lshl_add_u64 v[64:65], v[64:65], 0, s[44:45]
	global_load_lds_dwordx4 v[64:65], off
	global_load_lds_dwordx4 v[64:65], off offset:1024
	v_mfma_f32_32x32x16_bf16 v[166:181], v[202:205], v[74:77], v[166:181]
	ds_read_b128 v[202:205], v115 offset:32768
	s_mov_b32 m0, s54
	v_lshl_add_u64 v[66:67], v[66:67], 0, s[44:45]
	global_load_lds_dwordx4 v[66:67], off
	global_load_lds_dwordx4 v[66:67], off offset:1024
	v_mfma_f32_32x32x16_bf16 v[16:31], v[206:209], v[214:217], v[16:31]
	ds_read_b128 v[214:217], v119 offset:40960
	s_mov_b32 m0, s57
	v_lshl_add_u64 v[148:149], v[66:67], 0, s[72:73]
	global_load_lds_dwordx4 v[148:149], off
	global_load_lds_dwordx4 v[148:149], off offset:1024
	v_mfma_f32_32x32x16_bf16 v[0:15], v[206:209], v[244:247], v[0:15]
	ds_read_b128 v[244:247], v119 offset:43008
	v_mfma_f32_32x32x16_bf16 v[184:199], v[206:209], v[250:253], v[184:199]
	ds_read_b128 v[250:253], v122 offset:57344
	v_mfma_f32_32x32x16_bf16 v[226:241], v[206:209], v[74:77], v[226:241]
	ds_read_b128 v[206:209], v115 offset:34816
	ds_read_b128 v[74:77], v122 offset:59392
	s_waitcnt lgkmcnt(6)
	v_mfma_f32_32x32x16_bf16 v[48:63], v[110:113], v[132:135], v[48:63]
	v_mfma_f32_32x32x16_bf16 v[32:47], v[110:113], v[136:139], v[32:47]
	v_mfma_f32_32x32x16_bf16 v[150:165], v[110:113], v[140:143], v[150:165]
	v_mfma_f32_32x32x16_bf16 v[166:181], v[110:113], v[144:147], v[166:181]
	v_mfma_f32_32x32x16_bf16 v[16:31], v[128:131], v[132:135], v[16:31]
	v_mfma_f32_32x32x16_bf16 v[0:15], v[128:131], v[136:139], v[0:15]
	v_mfma_f32_32x32x16_bf16 v[184:199], v[128:131], v[140:143], v[184:199]
	v_mfma_f32_32x32x16_bf16 v[226:241], v[128:131], v[144:147], v[226:241]
	s_waitcnt vmcnt(6)
	s_waitcnt lgkmcnt(0)
	s_barrier
	ds_read_b128 v[110:113], v109
	ds_read_b128 v[132:135], v114 offset:8192
	v_mfma_f32_32x32x16_bf16 v[48:63], v[202:205], v[214:217], v[48:63]
	ds_read_b128 v[136:139], v114 offset:10240
	ds_read_b128 v[140:143], v114 offset:49152
	v_mfma_f32_32x32x16_bf16 v[32:47], v[202:205], v[244:247], v[32:47]
	ds_read_b128 v[144:147], v114 offset:51200
	ds_read_b128 v[128:131], v109 offset:2048
	v_mfma_f32_32x32x16_bf16 v[150:165], v[202:205], v[250:253], v[150:165]
	s_mov_b32 m0, s52
	v_lshl_add_u64 v[64:65], v[64:65], 0, s[44:45]
	global_load_lds_dwordx4 v[64:65], off
	global_load_lds_dwordx4 v[64:65], off offset:1024
	v_mfma_f32_32x32x16_bf16 v[166:181], v[202:205], v[74:77], v[166:181]
	ds_read_b128 v[202:205], v115
	s_mov_b32 m0, s55
	v_lshl_add_u64 v[66:67], v[66:67], 0, s[44:45]
	global_load_lds_dwordx4 v[66:67], off
	global_load_lds_dwordx4 v[66:67], off offset:1024
	v_mfma_f32_32x32x16_bf16 v[16:31], v[206:209], v[214:217], v[16:31]
	ds_read_b128 v[214:217], v119 offset:8192
	s_mov_b32 m0, s58
	v_lshl_add_u64 v[148:149], v[66:67], 0, s[72:73]
	global_load_lds_dwordx4 v[148:149], off
	global_load_lds_dwordx4 v[148:149], off offset:1024
	v_mfma_f32_32x32x16_bf16 v[0:15], v[206:209], v[244:247], v[0:15]
	ds_read_b128 v[244:247], v119 offset:10240
	v_mfma_f32_32x32x16_bf16 v[184:199], v[206:209], v[250:253], v[184:199]
	ds_read_b128 v[250:253], v119 offset:49152
	v_mfma_f32_32x32x16_bf16 v[226:241], v[206:209], v[74:77], v[226:241]
	ds_read_b128 v[206:209], v115 offset:2048
	ds_read_b128 v[74:77], v119 offset:51200
	s_waitcnt lgkmcnt(6)
	v_mfma_f32_32x32x16_bf16 v[48:63], v[110:113], v[132:135], v[48:63]
	v_mfma_f32_32x32x16_bf16 v[32:47], v[110:113], v[136:139], v[32:47]
	v_mfma_f32_32x32x16_bf16 v[150:165], v[110:113], v[140:143], v[150:165]
	v_mfma_f32_32x32x16_bf16 v[166:181], v[110:113], v[144:147], v[166:181]
	v_mfma_f32_32x32x16_bf16 v[16:31], v[128:131], v[132:135], v[16:31]
	v_mfma_f32_32x32x16_bf16 v[0:15], v[128:131], v[136:139], v[0:15]
	v_mfma_f32_32x32x16_bf16 v[184:199], v[128:131], v[140:143], v[184:199]
	v_mfma_f32_32x32x16_bf16 v[226:241], v[128:131], v[144:147], v[226:241]
	s_waitcnt vmcnt(6)
	s_waitcnt lgkmcnt(0)
	s_barrier
	ds_read_b128 v[110:113], v109 offset:16384
	ds_read_b128 v[132:135], v114 offset:24576
	v_mfma_f32_32x32x16_bf16 v[48:63], v[202:205], v[214:217], v[48:63]
	ds_read_b128 v[136:139], v114 offset:26624
	ds_read_b128 v[140:143], v121 offset:40960
	v_mfma_f32_32x32x16_bf16 v[32:47], v[202:205], v[244:247], v[32:47]
	ds_read_b128 v[144:147], v121 offset:43008
	ds_read_b128 v[128:131], v109 offset:18432
	v_mfma_f32_32x32x16_bf16 v[150:165], v[202:205], v[250:253], v[150:165]
	s_mov_b32 m0, s50
	v_lshl_add_u64 v[64:65], v[64:65], 0, s[44:45]
	global_load_lds_dwordx4 v[64:65], off
	global_load_lds_dwordx4 v[64:65], off offset:1024
	v_mfma_f32_32x32x16_bf16 v[166:181], v[202:205], v[74:77], v[166:181]
	ds_read_b128 v[202:205], v115 offset:16384
	s_mov_b32 m0, s53
	v_lshl_add_u64 v[66:67], v[66:67], 0, s[44:45]
	global_load_lds_dwordx4 v[66:67], off
	global_load_lds_dwordx4 v[66:67], off offset:1024
	v_mfma_f32_32x32x16_bf16 v[16:31], v[206:209], v[214:217], v[16:31]
	ds_read_b128 v[214:217], v119 offset:24576
	s_mov_b32 m0, s56
	v_lshl_add_u64 v[148:149], v[66:67], 0, s[72:73]
	global_load_lds_dwordx4 v[148:149], off
	global_load_lds_dwordx4 v[148:149], off offset:1024
	v_mfma_f32_32x32x16_bf16 v[0:15], v[206:209], v[244:247], v[0:15]
	ds_read_b128 v[244:247], v119 offset:26624
	v_mfma_f32_32x32x16_bf16 v[184:199], v[206:209], v[250:253], v[184:199]
	ds_read_b128 v[250:253], v122 offset:40960
	v_mfma_f32_32x32x16_bf16 v[226:241], v[206:209], v[74:77], v[226:241]
	ds_read_b128 v[206:209], v115 offset:18432
	ds_read_b128 v[74:77], v122 offset:43008
	s_waitcnt lgkmcnt(6)
	v_mfma_f32_32x32x16_bf16 v[48:63], v[110:113], v[132:135], v[48:63]
	v_mfma_f32_32x32x16_bf16 v[32:47], v[110:113], v[136:139], v[32:47]
	v_mfma_f32_32x32x16_bf16 v[150:165], v[110:113], v[140:143], v[150:165]
	v_mfma_f32_32x32x16_bf16 v[166:181], v[110:113], v[144:147], v[166:181]
	v_mfma_f32_32x32x16_bf16 v[16:31], v[128:131], v[132:135], v[16:31]
	v_mfma_f32_32x32x16_bf16 v[0:15], v[128:131], v[136:139], v[0:15]
	v_mfma_f32_32x32x16_bf16 v[184:199], v[128:131], v[140:143], v[184:199]
	v_mfma_f32_32x32x16_bf16 v[226:241], v[128:131], v[144:147], v[226:241]
	s_waitcnt vmcnt(6)
	s_waitcnt lgkmcnt(0)
	s_barrier
	ds_read_b128 v[110:113], v109 offset:32768
	ds_read_b128 v[132:135], v114 offset:40960
	v_mfma_f32_32x32x16_bf16 v[48:63], v[202:205], v[214:217], v[48:63]
	ds_read_b128 v[136:139], v114 offset:43008
	ds_read_b128 v[140:143], v121 offset:57344
	v_mfma_f32_32x32x16_bf16 v[32:47], v[202:205], v[244:247], v[32:47]
	ds_read_b128 v[144:147], v121 offset:59392
	ds_read_b128 v[128:131], v109 offset:34816
	v_mfma_f32_32x32x16_bf16 v[150:165], v[202:205], v[250:253], v[150:165]
	s_mov_b32 m0, s51
	v_lshl_add_u64 v[64:65], v[64:65], 0, s[44:45]
	global_load_lds_dwordx4 v[64:65], off
	global_load_lds_dwordx4 v[64:65], off offset:1024
	v_mfma_f32_32x32x16_bf16 v[166:181], v[202:205], v[74:77], v[166:181]
	ds_read_b128 v[202:205], v115 offset:32768
	s_mov_b32 m0, s54
	v_lshl_add_u64 v[66:67], v[66:67], 0, s[44:45]
	global_load_lds_dwordx4 v[66:67], off
	global_load_lds_dwordx4 v[66:67], off offset:1024
	v_mfma_f32_32x32x16_bf16 v[16:31], v[206:209], v[214:217], v[16:31]
	ds_read_b128 v[214:217], v119 offset:40960
	s_mov_b32 m0, s57
	v_lshl_add_u64 v[148:149], v[66:67], 0, s[72:73]
	global_load_lds_dwordx4 v[148:149], off
	global_load_lds_dwordx4 v[148:149], off offset:1024
	v_mfma_f32_32x32x16_bf16 v[0:15], v[206:209], v[244:247], v[0:15]
	ds_read_b128 v[244:247], v119 offset:43008
	v_mfma_f32_32x32x16_bf16 v[184:199], v[206:209], v[250:253], v[184:199]
	ds_read_b128 v[250:253], v122 offset:57344
	v_mfma_f32_32x32x16_bf16 v[226:241], v[206:209], v[74:77], v[226:241]
	ds_read_b128 v[206:209], v115 offset:34816
	ds_read_b128 v[74:77], v122 offset:59392
	s_waitcnt lgkmcnt(6)
	v_mfma_f32_32x32x16_bf16 v[48:63], v[110:113], v[132:135], v[48:63]
	v_mfma_f32_32x32x16_bf16 v[32:47], v[110:113], v[136:139], v[32:47]
	v_mfma_f32_32x32x16_bf16 v[150:165], v[110:113], v[140:143], v[150:165]
	v_mfma_f32_32x32x16_bf16 v[166:181], v[110:113], v[144:147], v[166:181]
	v_mfma_f32_32x32x16_bf16 v[16:31], v[128:131], v[132:135], v[16:31]
	v_mfma_f32_32x32x16_bf16 v[0:15], v[128:131], v[136:139], v[0:15]
	v_mfma_f32_32x32x16_bf16 v[184:199], v[128:131], v[140:143], v[184:199]
	v_mfma_f32_32x32x16_bf16 v[226:241], v[128:131], v[144:147], v[226:241]
	s_waitcnt vmcnt(6)
	s_waitcnt lgkmcnt(0)
	s_barrier
	ds_read_b128 v[110:113], v109
	ds_read_b128 v[132:135], v114 offset:8192
	v_mfma_f32_32x32x16_bf16 v[48:63], v[202:205], v[214:217], v[48:63]
	ds_read_b128 v[136:139], v114 offset:10240
	ds_read_b128 v[140:143], v114 offset:49152
	v_mfma_f32_32x32x16_bf16 v[32:47], v[202:205], v[244:247], v[32:47]
	ds_read_b128 v[144:147], v114 offset:51200
	ds_read_b128 v[128:131], v109 offset:2048
	v_mfma_f32_32x32x16_bf16 v[150:165], v[202:205], v[250:253], v[150:165]
	s_mov_b32 m0, s52
	v_lshl_add_u64 v[64:65], v[64:65], 0, s[44:45]
	global_load_lds_dwordx4 v[64:65], off
	global_load_lds_dwordx4 v[64:65], off offset:1024
	v_mfma_f32_32x32x16_bf16 v[166:181], v[202:205], v[74:77], v[166:181]
	ds_read_b128 v[202:205], v115
	s_mov_b32 m0, s55
	v_lshl_add_u64 v[66:67], v[66:67], 0, s[44:45]
	global_load_lds_dwordx4 v[66:67], off
	global_load_lds_dwordx4 v[66:67], off offset:1024
	v_mfma_f32_32x32x16_bf16 v[16:31], v[206:209], v[214:217], v[16:31]
	ds_read_b128 v[214:217], v119 offset:8192
	s_mov_b32 m0, s58
	v_lshl_add_u64 v[148:149], v[66:67], 0, s[72:73]
	global_load_lds_dwordx4 v[148:149], off
	global_load_lds_dwordx4 v[148:149], off offset:1024
	v_mfma_f32_32x32x16_bf16 v[0:15], v[206:209], v[244:247], v[0:15]
	ds_read_b128 v[244:247], v119 offset:10240
	v_mfma_f32_32x32x16_bf16 v[184:199], v[206:209], v[250:253], v[184:199]
	ds_read_b128 v[250:253], v119 offset:49152
	v_mfma_f32_32x32x16_bf16 v[226:241], v[206:209], v[74:77], v[226:241]
	ds_read_b128 v[206:209], v115 offset:2048
	ds_read_b128 v[74:77], v119 offset:51200
	s_waitcnt lgkmcnt(6)
	v_mfma_f32_32x32x16_bf16 v[48:63], v[110:113], v[132:135], v[48:63]
	v_mfma_f32_32x32x16_bf16 v[32:47], v[110:113], v[136:139], v[32:47]
	v_mfma_f32_32x32x16_bf16 v[150:165], v[110:113], v[140:143], v[150:165]
	v_mfma_f32_32x32x16_bf16 v[166:181], v[110:113], v[144:147], v[166:181]
	v_mfma_f32_32x32x16_bf16 v[16:31], v[128:131], v[132:135], v[16:31]
	v_mfma_f32_32x32x16_bf16 v[0:15], v[128:131], v[136:139], v[0:15]
	v_mfma_f32_32x32x16_bf16 v[184:199], v[128:131], v[140:143], v[184:199]
	v_mfma_f32_32x32x16_bf16 v[226:241], v[128:131], v[144:147], v[226:241]
	s_waitcnt vmcnt(6)
	s_waitcnt lgkmcnt(0)
	s_barrier
	ds_read_b128 v[110:113], v109 offset:16384
	ds_read_b128 v[132:135], v114 offset:24576
	v_mfma_f32_32x32x16_bf16 v[48:63], v[202:205], v[214:217], v[48:63]
	ds_read_b128 v[136:139], v114 offset:26624
	ds_read_b128 v[140:143], v121 offset:40960
	v_mfma_f32_32x32x16_bf16 v[32:47], v[202:205], v[244:247], v[32:47]
	ds_read_b128 v[144:147], v121 offset:43008
	ds_read_b128 v[128:131], v109 offset:18432
	v_mfma_f32_32x32x16_bf16 v[150:165], v[202:205], v[250:253], v[150:165]
	s_mov_b32 m0, s50
	v_lshl_add_u64 v[64:65], v[64:65], 0, s[44:45]
	global_load_lds_dwordx4 v[64:65], off
	global_load_lds_dwordx4 v[64:65], off offset:1024
	v_mfma_f32_32x32x16_bf16 v[166:181], v[202:205], v[74:77], v[166:181]
	ds_read_b128 v[202:205], v115 offset:16384
	s_mov_b32 m0, s53
	v_lshl_add_u64 v[66:67], v[66:67], 0, s[44:45]
	global_load_lds_dwordx4 v[66:67], off
	global_load_lds_dwordx4 v[66:67], off offset:1024
	v_mfma_f32_32x32x16_bf16 v[16:31], v[206:209], v[214:217], v[16:31]
	ds_read_b128 v[214:217], v119 offset:24576
	s_mov_b32 m0, s56
	v_lshl_add_u64 v[148:149], v[66:67], 0, s[72:73]
	global_load_lds_dwordx4 v[148:149], off
	global_load_lds_dwordx4 v[148:149], off offset:1024
	v_mfma_f32_32x32x16_bf16 v[0:15], v[206:209], v[244:247], v[0:15]
	ds_read_b128 v[244:247], v119 offset:26624
	v_mfma_f32_32x32x16_bf16 v[184:199], v[206:209], v[250:253], v[184:199]
	ds_read_b128 v[250:253], v122 offset:40960
	v_mfma_f32_32x32x16_bf16 v[226:241], v[206:209], v[74:77], v[226:241]
	ds_read_b128 v[206:209], v115 offset:18432
	ds_read_b128 v[74:77], v122 offset:43008
	s_waitcnt lgkmcnt(6)
	v_mfma_f32_32x32x16_bf16 v[48:63], v[110:113], v[132:135], v[48:63]
	v_mfma_f32_32x32x16_bf16 v[32:47], v[110:113], v[136:139], v[32:47]
	v_mfma_f32_32x32x16_bf16 v[150:165], v[110:113], v[140:143], v[150:165]
	v_mfma_f32_32x32x16_bf16 v[166:181], v[110:113], v[144:147], v[166:181]
	v_mfma_f32_32x32x16_bf16 v[16:31], v[128:131], v[132:135], v[16:31]
	v_mfma_f32_32x32x16_bf16 v[0:15], v[128:131], v[136:139], v[0:15]
	v_mfma_f32_32x32x16_bf16 v[184:199], v[128:131], v[140:143], v[184:199]
	v_mfma_f32_32x32x16_bf16 v[226:241], v[128:131], v[144:147], v[226:241]
	s_waitcnt vmcnt(6)
	s_waitcnt lgkmcnt(0)
	s_barrier
	ds_read_b128 v[110:113], v109 offset:32768
	ds_read_b128 v[132:135], v114 offset:40960
	v_mfma_f32_32x32x16_bf16 v[48:63], v[202:205], v[214:217], v[48:63]
	ds_read_b128 v[136:139], v114 offset:43008
	ds_read_b128 v[140:143], v121 offset:57344
	v_mfma_f32_32x32x16_bf16 v[32:47], v[202:205], v[244:247], v[32:47]
	ds_read_b128 v[144:147], v121 offset:59392
	ds_read_b128 v[128:131], v109 offset:34816
	v_mfma_f32_32x32x16_bf16 v[150:165], v[202:205], v[250:253], v[150:165]
	s_mov_b32 m0, s51
	v_lshl_add_u64 v[64:65], v[64:65], 0, s[44:45]
	global_load_lds_dwordx4 v[64:65], off
	global_load_lds_dwordx4 v[64:65], off offset:1024
	v_mfma_f32_32x32x16_bf16 v[166:181], v[202:205], v[74:77], v[166:181]
	ds_read_b128 v[202:205], v115 offset:32768
	s_mov_b32 m0, s54
	v_lshl_add_u64 v[66:67], v[66:67], 0, s[44:45]
	global_load_lds_dwordx4 v[66:67], off
	global_load_lds_dwordx4 v[66:67], off offset:1024
	v_mfma_f32_32x32x16_bf16 v[16:31], v[206:209], v[214:217], v[16:31]
	ds_read_b128 v[214:217], v119 offset:40960
	s_mov_b32 m0, s57
	v_lshl_add_u64 v[148:149], v[66:67], 0, s[72:73]
	global_load_lds_dwordx4 v[148:149], off
	global_load_lds_dwordx4 v[148:149], off offset:1024
	v_mfma_f32_32x32x16_bf16 v[0:15], v[206:209], v[244:247], v[0:15]
	ds_read_b128 v[244:247], v119 offset:43008
	v_mfma_f32_32x32x16_bf16 v[184:199], v[206:209], v[250:253], v[184:199]
	ds_read_b128 v[250:253], v122 offset:57344
	v_mfma_f32_32x32x16_bf16 v[226:241], v[206:209], v[74:77], v[226:241]
	ds_read_b128 v[206:209], v115 offset:34816
	ds_read_b128 v[74:77], v122 offset:59392
	s_waitcnt lgkmcnt(6)
	v_mfma_f32_32x32x16_bf16 v[48:63], v[110:113], v[132:135], v[48:63]
	v_mfma_f32_32x32x16_bf16 v[32:47], v[110:113], v[136:139], v[32:47]
	v_mfma_f32_32x32x16_bf16 v[150:165], v[110:113], v[140:143], v[150:165]
	v_mfma_f32_32x32x16_bf16 v[166:181], v[110:113], v[144:147], v[166:181]
	v_mfma_f32_32x32x16_bf16 v[16:31], v[128:131], v[132:135], v[16:31]
	v_mfma_f32_32x32x16_bf16 v[0:15], v[128:131], v[136:139], v[0:15]
	v_mfma_f32_32x32x16_bf16 v[184:199], v[128:131], v[140:143], v[184:199]
	v_mfma_f32_32x32x16_bf16 v[226:241], v[128:131], v[144:147], v[226:241]
	s_waitcnt vmcnt(6)
	s_waitcnt lgkmcnt(0)
	s_barrier
	ds_read_b128 v[110:113], v109
	ds_read_b128 v[132:135], v114 offset:8192
	v_mfma_f32_32x32x16_bf16 v[48:63], v[202:205], v[214:217], v[48:63]
	ds_read_b128 v[136:139], v114 offset:10240
	ds_read_b128 v[140:143], v114 offset:49152
	v_mfma_f32_32x32x16_bf16 v[32:47], v[202:205], v[244:247], v[32:47]
	ds_read_b128 v[144:147], v114 offset:51200
	ds_read_b128 v[128:131], v109 offset:2048
	v_mfma_f32_32x32x16_bf16 v[150:165], v[202:205], v[250:253], v[150:165]
	v_mfma_f32_32x32x16_bf16 v[166:181], v[202:205], v[74:77], v[166:181]
	ds_read_b128 v[202:205], v115
	v_mfma_f32_32x32x16_bf16 v[16:31], v[206:209], v[214:217], v[16:31]
	ds_read_b128 v[214:217], v119 offset:8192
	v_mfma_f32_32x32x16_bf16 v[0:15], v[206:209], v[244:247], v[0:15]
	ds_read_b128 v[244:247], v119 offset:10240
	v_mfma_f32_32x32x16_bf16 v[184:199], v[206:209], v[250:253], v[184:199]
	ds_read_b128 v[250:253], v119 offset:49152
	v_mfma_f32_32x32x16_bf16 v[226:241], v[206:209], v[74:77], v[226:241]
	ds_read_b128 v[206:209], v115 offset:2048
	ds_read_b128 v[74:77], v119 offset:51200
	s_waitcnt lgkmcnt(6)
	v_mfma_f32_32x32x16_bf16 v[48:63], v[110:113], v[132:135], v[48:63]
	v_mfma_f32_32x32x16_bf16 v[32:47], v[110:113], v[136:139], v[32:47]
	v_mfma_f32_32x32x16_bf16 v[150:165], v[110:113], v[140:143], v[150:165]
	v_mfma_f32_32x32x16_bf16 v[166:181], v[110:113], v[144:147], v[166:181]
	v_mfma_f32_32x32x16_bf16 v[16:31], v[128:131], v[132:135], v[16:31]
	v_mfma_f32_32x32x16_bf16 v[0:15], v[128:131], v[136:139], v[0:15]
	v_mfma_f32_32x32x16_bf16 v[184:199], v[128:131], v[140:143], v[184:199]
	v_mfma_f32_32x32x16_bf16 v[226:241], v[128:131], v[144:147], v[226:241]
	s_waitcnt vmcnt(0)
	s_waitcnt lgkmcnt(0)
	s_barrier
	ds_read_b128 v[110:113], v109 offset:16384
	ds_read_b128 v[132:135], v114 offset:24576
	v_mfma_f32_32x32x16_bf16 v[48:63], v[202:205], v[214:217], v[48:63]
	ds_read_b128 v[136:139], v114 offset:26624
	ds_read_b128 v[140:143], v121 offset:40960
	v_mfma_f32_32x32x16_bf16 v[32:47], v[202:205], v[244:247], v[32:47]
	ds_read_b128 v[144:147], v121 offset:43008
	ds_read_b128 v[128:131], v109 offset:18432
	v_mfma_f32_32x32x16_bf16 v[150:165], v[202:205], v[250:253], v[150:165]
	v_mfma_f32_32x32x16_bf16 v[166:181], v[202:205], v[74:77], v[166:181]
	ds_read_b128 v[202:205], v115 offset:16384
	v_mfma_f32_32x32x16_bf16 v[16:31], v[206:209], v[214:217], v[16:31]
	ds_read_b128 v[214:217], v119 offset:24576
	v_mfma_f32_32x32x16_bf16 v[0:15], v[206:209], v[244:247], v[0:15]
	ds_read_b128 v[244:247], v119 offset:26624
	v_mfma_f32_32x32x16_bf16 v[184:199], v[206:209], v[250:253], v[184:199]
	ds_read_b128 v[250:253], v122 offset:40960
	v_mfma_f32_32x32x16_bf16 v[226:241], v[206:209], v[74:77], v[226:241]
	ds_read_b128 v[206:209], v115 offset:18432
	ds_read_b128 v[74:77], v122 offset:43008
	s_waitcnt lgkmcnt(6)
	v_mfma_f32_32x32x16_bf16 v[48:63], v[110:113], v[132:135], v[48:63]
	v_mfma_f32_32x32x16_bf16 v[32:47], v[110:113], v[136:139], v[32:47]
	v_mfma_f32_32x32x16_bf16 v[150:165], v[110:113], v[140:143], v[150:165]
	v_mfma_f32_32x32x16_bf16 v[166:181], v[110:113], v[144:147], v[166:181]
	v_mfma_f32_32x32x16_bf16 v[16:31], v[128:131], v[132:135], v[16:31]
	v_mfma_f32_32x32x16_bf16 v[0:15], v[128:131], v[136:139], v[0:15]
	v_mfma_f32_32x32x16_bf16 v[184:199], v[128:131], v[140:143], v[184:199]
	v_mfma_f32_32x32x16_bf16 v[226:241], v[128:131], v[144:147], v[226:241]
	s_waitcnt lgkmcnt(0)
	v_mfma_f32_32x32x16_bf16 v[48:63], v[202:205], v[214:217], v[48:63]
	v_mfma_f32_32x32x16_bf16 v[32:47], v[202:205], v[244:247], v[32:47]
	v_mfma_f32_32x32x16_bf16 v[150:165], v[202:205], v[250:253], v[150:165]
	v_mfma_f32_32x32x16_bf16 v[166:181], v[202:205], v[74:77], v[166:181]
	v_mfma_f32_32x32x16_bf16 v[16:31], v[206:209], v[214:217], v[16:31]
	v_mfma_f32_32x32x16_bf16 v[0:15], v[206:209], v[244:247], v[0:15]
	v_mfma_f32_32x32x16_bf16 v[184:199], v[206:209], v[250:253], v[184:199]
	v_mfma_f32_32x32x16_bf16 v[226:241], v[206:209], v[74:77], v[226:241]
	v_add_u32_e32 v77, 0x4400, v88
	v_add_u32_e32 v76, 0x6000, v88
	v_add_u32_e32 v75, 0x6400, v88
	v_add_u32_e32 v74, 0x8000, v88
	s_branch .Lgu_post

.Lgu_post:
	s_and_saveexec_b64 s[18:19], s[36:37]
	s_cbranch_execz .LBB0_136
	s_mov_b32 s1, 0x800000
	v_mul_f32_e32 v64, 0x4b800000, v72
	v_cmp_gt_f32_e32 vcc, s1, v72
	s_nop 1
	v_cndmask_b32_e32 v64, v72, v64, vcc
	v_rsq_f32_e32 v64, v64
	s_nop 0
	v_mul_f32_e32 v65, 0x45800000, v64
	v_cndmask_b32_e32 v64, v64, v65, vcc
	ds_write_b32 v93, v64

.LBB0_139:
	s_cmp_eq_u32 s13, 8
	s_cbranch_scc0 .Lgu_orig2
	s_cmp_lt_u32 s22, 0x80
	s_cbranch_scc0 .Ldec_s2
	s_mul_hi_u32 s1, s22, 0x2aaaaaab
	s_mul_i32 s15, s1, 6
	s_sub_i32 s15, s22, s15
	s_lshl_b32 s1, s1, 1
	s_branch .Ldec_e2

.Ldec_e2:
	s_lshl_b32 s38, s15, 3
	s_and_b32 s15, s74, 7
	s_or_b32 s38, s38, s15
	s_lshl_b32 s38, s38, 7
	s_lshl_b32 s35, s1, 7
	s_add_i32 s22, s22, 64
	s_mov_b64 s[16:17], -1
	s_mov_b64 s[10:11], -1
	s_branch .LBB0_128

	.amdhsa_kernel _Z14fwd_megakernel6Params
		.amdhsa_group_segment_fixed_size 81920
		.amdhsa_private_segment_fixed_size 0
		.amdhsa_kernarg_size 480
		.amdhsa_user_sgpr_count 2
		.amdhsa_user_sgpr_dispatch_ptr 0
		.amdhsa_user_sgpr_queue_ptr 0
		.amdhsa_user_sgpr_kernarg_segment_ptr 1
		.amdhsa_user_sgpr_dispatch_id 0
		.amdhsa_user_sgpr_kernarg_preload_length 0
		.amdhsa_user_sgpr_kernarg_preload_offset 0
		.amdhsa_user_sgpr_private_segment_size 0
		.amdhsa_uses_dynamic_stack 0
		.amdhsa_enable_private_segment 0
		.amdhsa_system_sgpr_workgroup_id_x 1
		.amdhsa_system_sgpr_workgroup_id_y 0
		.amdhsa_system_sgpr_workgroup_id_z 0
		.amdhsa_system_sgpr_workgroup_info 0
		.amdhsa_system_vgpr_workitem_id 2
		.amdhsa_next_free_vgpr 256
		.amdhsa_next_free_sgpr 100
		.amdhsa_accum_offset 256
		.amdhsa_reserve_vcc 1
		.amdhsa_float_round_mode_32 0
		.amdhsa_float_round_mode_16_64 0
		.amdhsa_float_denorm_mode_32 3
		.amdhsa_float_denorm_mode_16_64 3
		.amdhsa_dx10_clamp 1
		.amdhsa_ieee_mode 1
		.amdhsa_fp16_overflow 0
		.amdhsa_tg_split 0
		.amdhsa_exception_fp_ieee_invalid_op 0
		.amdhsa_exception_fp_denorm_src 0
		.amdhsa_exception_fp_ieee_div_zero 0
		.amdhsa_exception_fp_ieee_overflow 0
		.amdhsa_exception_fp_ieee_underflow 0
		.amdhsa_exception_fp_ieee_inexact 0
		.amdhsa_exception_int_div_zero 0
	.end_amdhsa_kernel

amdhsa.kernels:
  - .agpr_count:     0
    .args:
      - .offset:         0
        .size:           224
        .value_kind:     by_value
      - .offset:         224
        .size:           4
        .value_kind:     hidden_block_count_x
      - .offset:         228
        .size:           4
        .value_kind:     hidden_block_count_y
      - .offset:         232
        .size:           4
        .value_kind:     hidden_block_count_z
      - .offset:         236
        .size:           2
        .value_kind:     hidden_group_size_x
      - .offset:         238
        .size:           2
        .value_kind:     hidden_group_size_y
      - .offset:         240
        .size:           2
        .value_kind:     hidden_group_size_z
      - .offset:         242
        .size:           2
        .value_kind:     hidden_remainder_x
      - .offset:         244
        .size:           2
        .value_kind:     hidden_remainder_y
      - .offset:         246
        .size:           2
        .value_kind:     hidden_remainder_z
      - .offset:         264
        .size:           8
        .value_kind:     hidden_global_offset_x
      - .offset:         272
        .size:           8
        .value_kind:     hidden_global_offset_y
      - .offset:         280
        .size:           8
        .value_kind:     hidden_global_offset_z
      - .offset:         288
        .size:           2
        .value_kind:     hidden_grid_dims
      - .offset:         312
        .size:           8
        .value_kind:     hidden_multigrid_sync_arg
    .group_segment_fixed_size: 81920
    .kernarg_segment_align: 8
    .kernarg_segment_size: 480
    .language:       OpenCL C
    .language_version:
      - 2
      - 0
    .max_flat_workgroup_size: 256
    .name:           _Z14fwd_megakernel6Params
    .private_segment_fixed_size: 0
    .sgpr_count:     106
    .sgpr_spill_count: 107
    .symbol:         _Z14fwd_megakernel6Params.kd
    .uniform_work_group_size: 1
    .uses_dynamic_stack: false
    .vgpr_count:     256
    .vgpr_spill_count: 0
    .wavefront_size: 64
